# K-loop alignment padding: runs reduced mod 64 bytes and the rest jumped over by one s_branch instead of executed as nops
# speedup vs baseline: 1.0030x; 1.0003x over previous
.LBB0_287:
	s_ashr_i32 s21, s20, 31
	s_lshl_b64 s[22:23], s[20:21], 19
	s_add_u32 s22, s80, s22
	s_addc_u32 s23, s81, s23
	s_and_b64 s[24:25], s[6:7], exec
	s_cselect_b32 s21, s23, s29
	s_cselect_b32 s36, s22, s28
	s_ashr_i32 s19, s18, 31
	s_lshl_b64 s[24:25], s[18:19], 19
	s_add_u32 s24, s40, s24
	s_addc_u32 s25, s41, s25
	s_and_b64 s[34:35], s[6:7], exec
	s_cselect_b32 s19, s25, s31
	s_cselect_b32 s37, s24, s30
	s_add_u32 s38, s30, 0x100
	s_addc_u32 s39, s31, 0
	s_add_u32 s28, s28, 0x40080
	s_addc_u32 s29, s29, 0
	s_mov_b32 s55, -2
	s_add_u32 s30, s28, 0xfffc0080
	s_addc_u32 s31, s29, -1
	s_add_i32 s56, 0, 0x10000
	s_cmp_eq_u32 s55, 12
	s_cselect_b32 s35, s21, s31
	s_cselect_b32 s34, s36, s30
	s_cselect_b32 s31, s19, s39
	s_cselect_b32 s30, s37, s38
	s_add_i32 s58, 0, 0x14000
	v_add_u32_e32 v166, s56, v147
	v_add_u32_e32 v182, s58, v147
	ds_read_b128 v[142:145], v166
	ds_read_b128 v[158:161], v166 offset:1024
	ds_read_b128 v[162:165], v166 offset:2048
	ds_read_b128 v[166:169], v166 offset:3072
	ds_read_b128 v[170:173], v182
	ds_read_b128 v[174:177], v182 offset:1024
	ds_read_b128 v[178:181], v182 offset:2048
	ds_read_b128 v[182:185], v182 offset:3072
	v_lshl_add_u64 v[224:225], s[28:29], 0, v[140:141]
	s_add_i32 m0, s44, 0xc000
	ds_read_b128 v[186:189], v157
	ds_read_b128 v[190:193], v157 offset:1024
	ds_read_b128 v[194:197], v157 offset:2048
	ds_read_b128 v[198:201], v157 offset:3072
	ds_read_b128 v[202:205], v157 offset:4096
	ds_read_b128 v[206:209], v157 offset:5120
	ds_read_b128 v[220:223], v157 offset:6144
	ds_read_b128 v[236:239], v157 offset:7168
	global_load_lds_dwordx4 v[224:225], off
	v_lshl_add_u64 v[224:225], s[28:29], 0, v[138:139]
	s_add_i32 m0, s44, 0xe000
	s_nop 0
	global_load_lds_dwordx4 v[224:225], off
	s_nop 0
	s_nop 0
	s_nop 0
	s_waitcnt vmcnt(8)
	s_waitcnt lgkmcnt(0)
	s_barrier
	s_waitcnt lgkmcnt(0)
	v_mfma_f32_16x16x32_bf16 v[126:129], v[142:145], v[186:189], 0
	v_mfma_f32_16x16x32_bf16 v[122:125], v[162:165], v[186:189], 0
	v_mfma_f32_16x16x32_bf16 v[110:113], v[142:145], v[194:197], 0
	v_mfma_f32_16x16x32_bf16 v[106:109], v[162:165], v[194:197], 0
	v_mfma_f32_16x16x32_bf16 v[94:97], v[142:145], v[202:205], 0
	v_mfma_f32_16x16x32_bf16 v[90:93], v[162:165], v[202:205], 0
	v_mfma_f32_16x16x32_bf16 v[78:81], v[142:145], v[220:223], 0
	v_mfma_f32_16x16x32_bf16 v[74:77], v[162:165], v[220:223], 0
	v_mfma_f32_16x16x32_bf16 v[126:129], v[158:161], v[190:193], v[126:129]
	v_mfma_f32_16x16x32_bf16 v[122:125], v[166:169], v[190:193], v[122:125]
	v_mfma_f32_16x16x32_bf16 v[110:113], v[158:161], v[198:201], v[110:113]
	v_mfma_f32_16x16x32_bf16 v[106:109], v[166:169], v[198:201], v[106:109]
	v_mfma_f32_16x16x32_bf16 v[94:97], v[158:161], v[206:209], v[94:97]
	v_mfma_f32_16x16x32_bf16 v[90:93], v[166:169], v[206:209], v[90:93]
	v_mfma_f32_16x16x32_bf16 v[78:81], v[158:161], v[236:239], v[78:81]
	v_mfma_f32_16x16x32_bf16 v[74:77], v[166:169], v[236:239], v[74:77]
	v_mfma_f32_16x16x32_bf16 v[118:121], v[170:173], v[186:189], 0
	v_mfma_f32_16x16x32_bf16 v[114:117], v[178:181], v[186:189], 0
	v_mfma_f32_16x16x32_bf16 v[102:105], v[170:173], v[194:197], 0
	v_mfma_f32_16x16x32_bf16 v[98:101], v[178:181], v[194:197], 0
	v_mfma_f32_16x16x32_bf16 v[86:89], v[170:173], v[202:205], 0
	v_mfma_f32_16x16x32_bf16 v[82:85], v[178:181], v[202:205], 0
	v_mfma_f32_16x16x32_bf16 v[70:73], v[170:173], v[220:223], 0
	v_mfma_f32_16x16x32_bf16 v[66:69], v[178:181], v[220:223], 0
	v_mfma_f32_16x16x32_bf16 v[118:121], v[174:177], v[190:193], v[118:121]
	v_mfma_f32_16x16x32_bf16 v[114:117], v[182:185], v[190:193], v[114:117]
	v_mfma_f32_16x16x32_bf16 v[102:105], v[174:177], v[198:201], v[102:105]
	v_mfma_f32_16x16x32_bf16 v[98:101], v[182:185], v[198:201], v[98:101]
	v_mfma_f32_16x16x32_bf16 v[86:89], v[174:177], v[206:209], v[86:89]
	v_mfma_f32_16x16x32_bf16 v[82:85], v[182:185], v[206:209], v[82:85]
	v_mfma_f32_16x16x32_bf16 v[70:73], v[174:177], v[236:239], v[70:73]
	v_mfma_f32_16x16x32_bf16 v[66:69], v[182:185], v[236:239], v[66:69]
	s_barrier
	s_add_i32 s56, s56, s27
	v_lshl_add_u64 v[224:225], s[30:31], 0, v[132:133]
	s_mov_b32 m0, s56
	ds_read_b128 v[186:189], v157 offset:16384
	ds_read_b128 v[190:193], v157 offset:17408
	ds_read_b128 v[194:197], v157 offset:18432
	ds_read_b128 v[198:201], v157 offset:19456
	ds_read_b128 v[202:205], v157 offset:20480
	ds_read_b128 v[206:209], v157 offset:21504
	ds_read_b128 v[220:223], v157 offset:22528
	ds_read_b128 v[236:239], v157 offset:23552
	global_load_lds_dwordx4 v[224:225], off
	s_add_i32 m0, s56, 0x2000
	s_add_u32 s56, s30, 0x40000
	v_lshl_add_u64 v[230:231], s[30:31], 0, v[136:137]
	s_addc_u32 s57, s31, 0
	s_add_i32 s58, s58, s27
	global_load_lds_dwordx4 v[230:231], off
	v_lshl_add_u64 v[240:241], s[56:57], 0, v[132:133]
	s_mov_b32 m0, s58
	v_lshl_add_u64 v[242:243], s[34:35], 0, v[134:135]
	global_load_lds_dwordx4 v[240:241], off
	v_lshl_add_u64 v[240:241], s[56:57], 0, v[136:137]
	s_add_i32 m0, s58, 0x2000
	s_nop 0
	global_load_lds_dwordx4 v[240:241], off
	v_lshl_add_u64 v[240:241], s[34:35], 0, v[130:131]
	s_mov_b32 m0, s44
	s_nop 0
	global_load_lds_dwordx4 v[240:241], off
	s_mov_b32 m0, s45
	s_nop 0
	global_load_lds_dwordx4 v[242:243], off
	s_nop 0
	s_nop 0
	s_nop 0
	s_waitcnt vmcnt(8)
	s_waitcnt lgkmcnt(0)
	s_barrier
	s_waitcnt lgkmcnt(0)
	v_mfma_f32_16x16x32_bf16 v[62:65], v[142:145], v[186:189], 0
	v_mfma_f32_16x16x32_bf16 v[58:61], v[162:165], v[186:189], 0
	v_mfma_f32_16x16x32_bf16 v[46:49], v[142:145], v[194:197], 0
	v_mfma_f32_16x16x32_bf16 v[42:45], v[162:165], v[194:197], 0
	v_mfma_f32_16x16x32_bf16 v[30:33], v[142:145], v[202:205], 0
	v_mfma_f32_16x16x32_bf16 v[26:29], v[162:165], v[202:205], 0
	v_mfma_f32_16x16x32_bf16 v[14:17], v[142:145], v[220:223], 0
	v_mfma_f32_16x16x32_bf16 v[10:13], v[162:165], v[220:223], 0
	v_mfma_f32_16x16x32_bf16 v[62:65], v[158:161], v[190:193], v[62:65]
	v_mfma_f32_16x16x32_bf16 v[58:61], v[166:169], v[190:193], v[58:61]
	v_mfma_f32_16x16x32_bf16 v[46:49], v[158:161], v[198:201], v[46:49]
	v_mfma_f32_16x16x32_bf16 v[42:45], v[166:169], v[198:201], v[42:45]
	v_mfma_f32_16x16x32_bf16 v[30:33], v[158:161], v[206:209], v[30:33]
	v_mfma_f32_16x16x32_bf16 v[26:29], v[166:169], v[206:209], v[26:29]
	v_mfma_f32_16x16x32_bf16 v[14:17], v[158:161], v[236:239], v[14:17]
	v_mfma_f32_16x16x32_bf16 v[10:13], v[166:169], v[236:239], v[10:13]
	v_mfma_f32_16x16x32_bf16 v[54:57], v[170:173], v[186:189], 0
	v_mfma_f32_16x16x32_bf16 v[50:53], v[178:181], v[186:189], 0
	v_mfma_f32_16x16x32_bf16 v[38:41], v[170:173], v[194:197], 0
	v_mfma_f32_16x16x32_bf16 v[34:37], v[178:181], v[194:197], 0
	v_mfma_f32_16x16x32_bf16 v[22:25], v[170:173], v[202:205], 0
	v_mfma_f32_16x16x32_bf16 v[18:21], v[178:181], v[202:205], 0
	v_mfma_f32_16x16x32_bf16 v[6:9], v[170:173], v[220:223], 0
	v_mfma_f32_16x16x32_bf16 v[2:5], v[178:181], v[220:223], 0
	v_mfma_f32_16x16x32_bf16 v[54:57], v[174:177], v[190:193], v[54:57]
	v_mfma_f32_16x16x32_bf16 v[50:53], v[182:185], v[190:193], v[50:53]
	v_mfma_f32_16x16x32_bf16 v[38:41], v[174:177], v[198:201], v[38:41]
	v_mfma_f32_16x16x32_bf16 v[34:37], v[182:185], v[198:201], v[34:37]
	v_mfma_f32_16x16x32_bf16 v[22:25], v[174:177], v[206:209], v[22:25]
	v_mfma_f32_16x16x32_bf16 v[18:21], v[182:185], v[206:209], v[18:21]
	v_mfma_f32_16x16x32_bf16 v[6:9], v[174:177], v[236:239], v[6:9]
	v_mfma_f32_16x16x32_bf16 v[2:5], v[182:185], v[236:239], v[2:5]
	s_barrier
	s_add_i32 s56, 0, 0x18000
	s_add_i32 s57, 0, 0x1c000
	v_add_u32_e32 v166, s56, v147
	v_add_u32_e32 v182, s57, v147
	ds_read_b128 v[142:145], v166
	ds_read_b128 v[158:161], v166 offset:1024
	ds_read_b128 v[162:165], v166 offset:2048
	ds_read_b128 v[166:169], v166 offset:3072
	ds_read_b128 v[170:173], v182
	ds_read_b128 v[174:177], v182 offset:1024
	ds_read_b128 v[178:181], v182 offset:2048
	ds_read_b128 v[182:185], v182 offset:3072
	s_add_u32 s34, s34, 0x40000
	s_addc_u32 s35, s35, 0
	s_mov_b32 m0, s43
	v_lshl_add_u64 v[244:245], s[34:35], 0, v[130:131]
	ds_read_b128 v[186:189], v157 offset:32768
	ds_read_b128 v[190:193], v157 offset:33792
	ds_read_b128 v[194:197], v157 offset:34816
	ds_read_b128 v[198:201], v157 offset:35840
	ds_read_b128 v[202:205], v157 offset:36864
	ds_read_b128 v[206:209], v157 offset:37888
	ds_read_b128 v[220:223], v157 offset:38912
	ds_read_b128 v[236:239], v157 offset:39936
	global_load_lds_dwordx4 v[244:245], off
	v_lshl_add_u64 v[244:245], s[34:35], 0, v[134:135]
	s_mov_b32 m0, s46
	s_nop 0
	global_load_lds_dwordx4 v[244:245], off
	s_branch .Lpadj_0
	s_nop 0
	s_nop 0
	s_nop 0
	s_nop 0
	s_nop 0
	s_nop 0
.Lpadj_0:
	s_waitcnt vmcnt(8)
	s_waitcnt lgkmcnt(0)
	s_barrier
	s_waitcnt lgkmcnt(0)
	v_mfma_f32_16x16x32_bf16 v[126:129], v[142:145], v[186:189], v[126:129]
	v_mfma_f32_16x16x32_bf16 v[122:125], v[162:165], v[186:189], v[122:125]
	v_mfma_f32_16x16x32_bf16 v[110:113], v[142:145], v[194:197], v[110:113]
	v_mfma_f32_16x16x32_bf16 v[106:109], v[162:165], v[194:197], v[106:109]
	v_mfma_f32_16x16x32_bf16 v[94:97], v[142:145], v[202:205], v[94:97]
	v_mfma_f32_16x16x32_bf16 v[90:93], v[162:165], v[202:205], v[90:93]
	v_mfma_f32_16x16x32_bf16 v[78:81], v[142:145], v[220:223], v[78:81]
	v_mfma_f32_16x16x32_bf16 v[74:77], v[162:165], v[220:223], v[74:77]
	v_mfma_f32_16x16x32_bf16 v[126:129], v[158:161], v[190:193], v[126:129]
	v_mfma_f32_16x16x32_bf16 v[122:125], v[166:169], v[190:193], v[122:125]
	v_mfma_f32_16x16x32_bf16 v[110:113], v[158:161], v[198:201], v[110:113]
	v_mfma_f32_16x16x32_bf16 v[106:109], v[166:169], v[198:201], v[106:109]
	v_mfma_f32_16x16x32_bf16 v[94:97], v[158:161], v[206:209], v[94:97]
	v_mfma_f32_16x16x32_bf16 v[90:93], v[166:169], v[206:209], v[90:93]
	v_mfma_f32_16x16x32_bf16 v[78:81], v[158:161], v[236:239], v[78:81]
	v_mfma_f32_16x16x32_bf16 v[74:77], v[166:169], v[236:239], v[74:77]
	v_mfma_f32_16x16x32_bf16 v[118:121], v[170:173], v[186:189], v[118:121]
	v_mfma_f32_16x16x32_bf16 v[114:117], v[178:181], v[186:189], v[114:117]
	v_mfma_f32_16x16x32_bf16 v[102:105], v[170:173], v[194:197], v[102:105]
	v_mfma_f32_16x16x32_bf16 v[98:101], v[178:181], v[194:197], v[98:101]
	v_mfma_f32_16x16x32_bf16 v[86:89], v[170:173], v[202:205], v[86:89]
	v_mfma_f32_16x16x32_bf16 v[82:85], v[178:181], v[202:205], v[82:85]
	v_mfma_f32_16x16x32_bf16 v[70:73], v[170:173], v[220:223], v[70:73]
	v_mfma_f32_16x16x32_bf16 v[66:69], v[178:181], v[220:223], v[66:69]
	v_mfma_f32_16x16x32_bf16 v[118:121], v[174:177], v[190:193], v[118:121]
	v_mfma_f32_16x16x32_bf16 v[114:117], v[182:185], v[190:193], v[114:117]
	v_mfma_f32_16x16x32_bf16 v[102:105], v[174:177], v[198:201], v[102:105]
	v_mfma_f32_16x16x32_bf16 v[98:101], v[182:185], v[198:201], v[98:101]
	v_mfma_f32_16x16x32_bf16 v[86:89], v[174:177], v[206:209], v[86:89]
	v_mfma_f32_16x16x32_bf16 v[82:85], v[182:185], v[206:209], v[82:85]
	v_mfma_f32_16x16x32_bf16 v[70:73], v[174:177], v[236:239], v[70:73]
	v_mfma_f32_16x16x32_bf16 v[66:69], v[182:185], v[236:239], v[66:69]
	s_barrier
	s_add_i32 s34, s56, s27
	v_lshl_add_u64 v[224:225], v[224:225], 0, s[96:97]
	s_mov_b32 m0, s34
	ds_read_b128 v[186:189], v157 offset:49152
	ds_read_b128 v[190:193], v157 offset:50176
	ds_read_b128 v[194:197], v157 offset:51200
	ds_read_b128 v[198:201], v157 offset:52224
	ds_read_b128 v[202:205], v157 offset:53248
	ds_read_b128 v[206:209], v157 offset:54272
	ds_read_b128 v[220:223], v157 offset:55296
	ds_read_b128 v[236:239], v157 offset:56320
	global_load_lds_dwordx4 v[224:225], off
	s_add_i32 m0, s34, 0x2000
	s_add_u32 s30, s30, 0x40080
	v_lshl_add_u64 v[224:225], v[230:231], 0, s[96:97]
	s_addc_u32 s31, s31, 0
	s_add_i32 s34, s57, s27
	global_load_lds_dwordx4 v[224:225], off
	v_lshl_add_u64 v[224:225], s[30:31], 0, v[132:133]
	s_mov_b32 m0, s34
	s_nop 0
	global_load_lds_dwordx4 v[224:225], off
	v_lshl_add_u64 v[224:225], s[30:31], 0, v[136:137]
	s_add_i32 m0, s34, 0x2000
	s_nop 0
	global_load_lds_dwordx4 v[224:225], off
	v_lshl_add_u64 v[224:225], v[240:241], 0, s[96:97]
	s_mov_b32 m0, s47
	s_nop 0
	global_load_lds_dwordx4 v[224:225], off
	v_lshl_add_u64 v[224:225], v[242:243], 0, s[96:97]
	s_mov_b32 m0, s48
	s_nop 0
	global_load_lds_dwordx4 v[224:225], off
	s_nop 0
	s_nop 0
	s_waitcnt vmcnt(8)
	s_waitcnt lgkmcnt(0)
	s_barrier
	s_waitcnt lgkmcnt(0)
	v_mfma_f32_16x16x32_bf16 v[62:65], v[142:145], v[186:189], v[62:65]
	v_mfma_f32_16x16x32_bf16 v[58:61], v[162:165], v[186:189], v[58:61]
	v_mfma_f32_16x16x32_bf16 v[46:49], v[142:145], v[194:197], v[46:49]
	v_mfma_f32_16x16x32_bf16 v[42:45], v[162:165], v[194:197], v[42:45]
	v_mfma_f32_16x16x32_bf16 v[30:33], v[142:145], v[202:205], v[30:33]
	v_mfma_f32_16x16x32_bf16 v[26:29], v[162:165], v[202:205], v[26:29]
	v_mfma_f32_16x16x32_bf16 v[14:17], v[142:145], v[220:223], v[14:17]
	v_mfma_f32_16x16x32_bf16 v[10:13], v[162:165], v[220:223], v[10:13]
	v_mfma_f32_16x16x32_bf16 v[62:65], v[158:161], v[190:193], v[62:65]
	v_mfma_f32_16x16x32_bf16 v[58:61], v[166:169], v[190:193], v[58:61]
	v_mfma_f32_16x16x32_bf16 v[46:49], v[158:161], v[198:201], v[46:49]
	v_mfma_f32_16x16x32_bf16 v[42:45], v[166:169], v[198:201], v[42:45]
	v_mfma_f32_16x16x32_bf16 v[30:33], v[158:161], v[206:209], v[30:33]
	v_mfma_f32_16x16x32_bf16 v[26:29], v[166:169], v[206:209], v[26:29]
	v_mfma_f32_16x16x32_bf16 v[14:17], v[158:161], v[236:239], v[14:17]
	v_mfma_f32_16x16x32_bf16 v[10:13], v[166:169], v[236:239], v[10:13]
	v_mfma_f32_16x16x32_bf16 v[54:57], v[170:173], v[186:189], v[54:57]
	v_mfma_f32_16x16x32_bf16 v[50:53], v[178:181], v[186:189], v[50:53]
	v_mfma_f32_16x16x32_bf16 v[38:41], v[170:173], v[194:197], v[38:41]
	v_mfma_f32_16x16x32_bf16 v[34:37], v[178:181], v[194:197], v[34:37]
	v_mfma_f32_16x16x32_bf16 v[22:25], v[170:173], v[202:205], v[22:25]
	v_mfma_f32_16x16x32_bf16 v[18:21], v[178:181], v[202:205], v[18:21]
	v_mfma_f32_16x16x32_bf16 v[6:9], v[170:173], v[220:223], v[6:9]
	v_mfma_f32_16x16x32_bf16 v[2:5], v[178:181], v[220:223], v[2:5]
	v_mfma_f32_16x16x32_bf16 v[54:57], v[174:177], v[190:193], v[54:57]
	v_mfma_f32_16x16x32_bf16 v[50:53], v[182:185], v[190:193], v[50:53]
	v_mfma_f32_16x16x32_bf16 v[38:41], v[174:177], v[198:201], v[38:41]
	v_mfma_f32_16x16x32_bf16 v[34:37], v[182:185], v[198:201], v[34:37]
	v_mfma_f32_16x16x32_bf16 v[22:25], v[174:177], v[206:209], v[22:25]
	v_mfma_f32_16x16x32_bf16 v[18:21], v[182:185], v[206:209], v[18:21]
	v_mfma_f32_16x16x32_bf16 v[6:9], v[174:177], v[236:239], v[6:9]
	v_mfma_f32_16x16x32_bf16 v[2:5], v[182:185], v[236:239], v[2:5]
	s_barrier
	s_add_i32 s55, s55, 2
	s_add_u32 s38, s38, 0x100
	s_addc_u32 s39, s39, 0
	s_add_u32 s28, s28, 0x100
	s_addc_u32 s29, s29, 0
	s_cmp_gt_u32 s55, 13
.LBB0_288:
	s_add_u32 s30, s28, 0xfffc0080
	s_addc_u32 s31, s29, -1
	s_add_i32 s56, 0, 0x10000
	s_cmp_eq_u32 s55, 12
	s_cselect_b32 s35, s21, s31
	s_cselect_b32 s34, s36, s30
	s_cselect_b32 s31, s19, s39
	s_cselect_b32 s30, s37, s38
	s_add_i32 s58, 0, 0x14000
	v_add_u32_e32 v166, s56, v147
	v_add_u32_e32 v182, s58, v147
	ds_read_b128 v[142:145], v166
	ds_read_b128 v[158:161], v166 offset:1024
	ds_read_b128 v[162:165], v166 offset:2048
	ds_read_b128 v[166:169], v166 offset:3072
	ds_read_b128 v[170:173], v182
	ds_read_b128 v[174:177], v182 offset:1024
	ds_read_b128 v[178:181], v182 offset:2048
	ds_read_b128 v[182:185], v182 offset:3072
	v_lshl_add_u64 v[224:225], s[28:29], 0, v[140:141]
	s_add_i32 m0, s44, 0xc000
	ds_read_b128 v[186:189], v157
	ds_read_b128 v[190:193], v157 offset:1024
	ds_read_b128 v[194:197], v157 offset:2048
	ds_read_b128 v[198:201], v157 offset:3072
	ds_read_b128 v[202:205], v157 offset:4096
	ds_read_b128 v[206:209], v157 offset:5120
	ds_read_b128 v[220:223], v157 offset:6144
	ds_read_b128 v[236:239], v157 offset:7168
	global_load_lds_dwordx4 v[224:225], off
	v_lshl_add_u64 v[224:225], s[28:29], 0, v[138:139]
	s_add_i32 m0, s44, 0xe000
	s_nop 0
	global_load_lds_dwordx4 v[224:225], off
	s_branch .Lpadj_1
	s_nop 0
	s_nop 0
	s_nop 0
	s_nop 0
	s_nop 0
	s_nop 0
	s_nop 0
.Lpadj_1:
	s_waitcnt vmcnt(8)
	s_waitcnt lgkmcnt(0)
	s_barrier
	s_waitcnt lgkmcnt(0)
	v_mfma_f32_16x16x32_bf16 v[126:129], v[142:145], v[186:189], v[126:129]
	v_mfma_f32_16x16x32_bf16 v[122:125], v[162:165], v[186:189], v[122:125]
	v_mfma_f32_16x16x32_bf16 v[110:113], v[142:145], v[194:197], v[110:113]
	v_mfma_f32_16x16x32_bf16 v[106:109], v[162:165], v[194:197], v[106:109]
	v_mfma_f32_16x16x32_bf16 v[94:97], v[142:145], v[202:205], v[94:97]
	v_mfma_f32_16x16x32_bf16 v[90:93], v[162:165], v[202:205], v[90:93]
	v_mfma_f32_16x16x32_bf16 v[78:81], v[142:145], v[220:223], v[78:81]
	v_mfma_f32_16x16x32_bf16 v[74:77], v[162:165], v[220:223], v[74:77]
	v_mfma_f32_16x16x32_bf16 v[126:129], v[158:161], v[190:193], v[126:129]
	v_mfma_f32_16x16x32_bf16 v[122:125], v[166:169], v[190:193], v[122:125]
	v_mfma_f32_16x16x32_bf16 v[110:113], v[158:161], v[198:201], v[110:113]
	v_mfma_f32_16x16x32_bf16 v[106:109], v[166:169], v[198:201], v[106:109]
	v_mfma_f32_16x16x32_bf16 v[94:97], v[158:161], v[206:209], v[94:97]
	v_mfma_f32_16x16x32_bf16 v[90:93], v[166:169], v[206:209], v[90:93]
	v_mfma_f32_16x16x32_bf16 v[78:81], v[158:161], v[236:239], v[78:81]
	v_mfma_f32_16x16x32_bf16 v[74:77], v[166:169], v[236:239], v[74:77]
	v_mfma_f32_16x16x32_bf16 v[118:121], v[170:173], v[186:189], v[118:121]
	v_mfma_f32_16x16x32_bf16 v[114:117], v[178:181], v[186:189], v[114:117]
	v_mfma_f32_16x16x32_bf16 v[102:105], v[170:173], v[194:197], v[102:105]
	v_mfma_f32_16x16x32_bf16 v[98:101], v[178:181], v[194:197], v[98:101]
	v_mfma_f32_16x16x32_bf16 v[86:89], v[170:173], v[202:205], v[86:89]
	v_mfma_f32_16x16x32_bf16 v[82:85], v[178:181], v[202:205], v[82:85]
	v_mfma_f32_16x16x32_bf16 v[70:73], v[170:173], v[220:223], v[70:73]
	v_mfma_f32_16x16x32_bf16 v[66:69], v[178:181], v[220:223], v[66:69]
	v_mfma_f32_16x16x32_bf16 v[118:121], v[174:177], v[190:193], v[118:121]
	v_mfma_f32_16x16x32_bf16 v[114:117], v[182:185], v[190:193], v[114:117]
	v_mfma_f32_16x16x32_bf16 v[102:105], v[174:177], v[198:201], v[102:105]
	v_mfma_f32_16x16x32_bf16 v[98:101], v[182:185], v[198:201], v[98:101]
	v_mfma_f32_16x16x32_bf16 v[86:89], v[174:177], v[206:209], v[86:89]
	v_mfma_f32_16x16x32_bf16 v[82:85], v[182:185], v[206:209], v[82:85]
	v_mfma_f32_16x16x32_bf16 v[70:73], v[174:177], v[236:239], v[70:73]
	v_mfma_f32_16x16x32_bf16 v[66:69], v[182:185], v[236:239], v[66:69]
	s_barrier
	s_add_i32 s56, s56, s27
	v_lshl_add_u64 v[224:225], s[30:31], 0, v[132:133]
	s_mov_b32 m0, s56
	ds_read_b128 v[186:189], v157 offset:16384
	ds_read_b128 v[190:193], v157 offset:17408
	ds_read_b128 v[194:197], v157 offset:18432
	ds_read_b128 v[198:201], v157 offset:19456
	ds_read_b128 v[202:205], v157 offset:20480
	ds_read_b128 v[206:209], v157 offset:21504
	ds_read_b128 v[220:223], v157 offset:22528
	ds_read_b128 v[236:239], v157 offset:23552
	global_load_lds_dwordx4 v[224:225], off
	s_add_i32 m0, s56, 0x2000
	s_add_u32 s56, s30, 0x40000
	v_lshl_add_u64 v[230:231], s[30:31], 0, v[136:137]
	s_addc_u32 s57, s31, 0
	s_add_i32 s58, s58, s27
	global_load_lds_dwordx4 v[230:231], off
	v_lshl_add_u64 v[240:241], s[56:57], 0, v[132:133]
	s_mov_b32 m0, s58
	v_lshl_add_u64 v[242:243], s[34:35], 0, v[134:135]
	global_load_lds_dwordx4 v[240:241], off
	v_lshl_add_u64 v[240:241], s[56:57], 0, v[136:137]
	s_add_i32 m0, s58, 0x2000
	s_nop 0
	global_load_lds_dwordx4 v[240:241], off
	v_lshl_add_u64 v[240:241], s[34:35], 0, v[130:131]
	s_mov_b32 m0, s44
	s_nop 0
	global_load_lds_dwordx4 v[240:241], off
	s_mov_b32 m0, s45
	s_nop 0
	global_load_lds_dwordx4 v[242:243], off
	s_nop 0
	s_nop 0
	s_nop 0
	s_waitcnt vmcnt(8)
	s_waitcnt lgkmcnt(0)
	s_barrier
	s_waitcnt lgkmcnt(0)
	v_mfma_f32_16x16x32_bf16 v[62:65], v[142:145], v[186:189], v[62:65]
	v_mfma_f32_16x16x32_bf16 v[58:61], v[162:165], v[186:189], v[58:61]
	v_mfma_f32_16x16x32_bf16 v[46:49], v[142:145], v[194:197], v[46:49]
	v_mfma_f32_16x16x32_bf16 v[42:45], v[162:165], v[194:197], v[42:45]
	v_mfma_f32_16x16x32_bf16 v[30:33], v[142:145], v[202:205], v[30:33]
	v_mfma_f32_16x16x32_bf16 v[26:29], v[162:165], v[202:205], v[26:29]
	v_mfma_f32_16x16x32_bf16 v[14:17], v[142:145], v[220:223], v[14:17]
	v_mfma_f32_16x16x32_bf16 v[10:13], v[162:165], v[220:223], v[10:13]
	v_mfma_f32_16x16x32_bf16 v[62:65], v[158:161], v[190:193], v[62:65]
	v_mfma_f32_16x16x32_bf16 v[58:61], v[166:169], v[190:193], v[58:61]
	v_mfma_f32_16x16x32_bf16 v[46:49], v[158:161], v[198:201], v[46:49]
	v_mfma_f32_16x16x32_bf16 v[42:45], v[166:169], v[198:201], v[42:45]
	v_mfma_f32_16x16x32_bf16 v[30:33], v[158:161], v[206:209], v[30:33]
	v_mfma_f32_16x16x32_bf16 v[26:29], v[166:169], v[206:209], v[26:29]
	v_mfma_f32_16x16x32_bf16 v[14:17], v[158:161], v[236:239], v[14:17]
	v_mfma_f32_16x16x32_bf16 v[10:13], v[166:169], v[236:239], v[10:13]
	v_mfma_f32_16x16x32_bf16 v[54:57], v[170:173], v[186:189], v[54:57]
	v_mfma_f32_16x16x32_bf16 v[50:53], v[178:181], v[186:189], v[50:53]
	v_mfma_f32_16x16x32_bf16 v[38:41], v[170:173], v[194:197], v[38:41]
	v_mfma_f32_16x16x32_bf16 v[34:37], v[178:181], v[194:197], v[34:37]
	v_mfma_f32_16x16x32_bf16 v[22:25], v[170:173], v[202:205], v[22:25]
	v_mfma_f32_16x16x32_bf16 v[18:21], v[178:181], v[202:205], v[18:21]
	v_mfma_f32_16x16x32_bf16 v[6:9], v[170:173], v[220:223], v[6:9]
	v_mfma_f32_16x16x32_bf16 v[2:5], v[178:181], v[220:223], v[2:5]
	v_mfma_f32_16x16x32_bf16 v[54:57], v[174:177], v[190:193], v[54:57]
	v_mfma_f32_16x16x32_bf16 v[50:53], v[182:185], v[190:193], v[50:53]
	v_mfma_f32_16x16x32_bf16 v[38:41], v[174:177], v[198:201], v[38:41]
	v_mfma_f32_16x16x32_bf16 v[34:37], v[182:185], v[198:201], v[34:37]
	v_mfma_f32_16x16x32_bf16 v[22:25], v[174:177], v[206:209], v[22:25]
	v_mfma_f32_16x16x32_bf16 v[18:21], v[182:185], v[206:209], v[18:21]
	v_mfma_f32_16x16x32_bf16 v[6:9], v[174:177], v[236:239], v[6:9]
	v_mfma_f32_16x16x32_bf16 v[2:5], v[182:185], v[236:239], v[2:5]
	s_barrier
	s_add_i32 s56, 0, 0x18000
	s_add_i32 s57, 0, 0x1c000
	v_add_u32_e32 v166, s56, v147
	v_add_u32_e32 v182, s57, v147
	ds_read_b128 v[142:145], v166
	ds_read_b128 v[158:161], v166 offset:1024
	ds_read_b128 v[162:165], v166 offset:2048
	ds_read_b128 v[166:169], v166 offset:3072
	ds_read_b128 v[170:173], v182
	ds_read_b128 v[174:177], v182 offset:1024
	ds_read_b128 v[178:181], v182 offset:2048
	ds_read_b128 v[182:185], v182 offset:3072
	s_add_u32 s34, s34, 0x40000
	s_addc_u32 s35, s35, 0
	s_mov_b32 m0, s43
	v_lshl_add_u64 v[244:245], s[34:35], 0, v[130:131]
	ds_read_b128 v[186:189], v157 offset:32768
	ds_read_b128 v[190:193], v157 offset:33792
	ds_read_b128 v[194:197], v157 offset:34816
	ds_read_b128 v[198:201], v157 offset:35840
	ds_read_b128 v[202:205], v157 offset:36864
	ds_read_b128 v[206:209], v157 offset:37888
	ds_read_b128 v[220:223], v157 offset:38912
	ds_read_b128 v[236:239], v157 offset:39936
	global_load_lds_dwordx4 v[244:245], off
	v_lshl_add_u64 v[244:245], s[34:35], 0, v[134:135]
	s_mov_b32 m0, s46
	s_nop 0
	global_load_lds_dwordx4 v[244:245], off
	s_branch .Lpadj_2
	s_nop 0
	s_nop 0
	s_nop 0
	s_nop 0
	s_nop 0
	s_nop 0
.Lpadj_2:
	s_waitcnt vmcnt(8)
	s_waitcnt lgkmcnt(0)
	s_barrier
	s_waitcnt lgkmcnt(0)
	v_mfma_f32_16x16x32_bf16 v[126:129], v[142:145], v[186:189], v[126:129]
	v_mfma_f32_16x16x32_bf16 v[122:125], v[162:165], v[186:189], v[122:125]
	v_mfma_f32_16x16x32_bf16 v[110:113], v[142:145], v[194:197], v[110:113]
	v_mfma_f32_16x16x32_bf16 v[106:109], v[162:165], v[194:197], v[106:109]
	v_mfma_f32_16x16x32_bf16 v[94:97], v[142:145], v[202:205], v[94:97]
	v_mfma_f32_16x16x32_bf16 v[90:93], v[162:165], v[202:205], v[90:93]
	v_mfma_f32_16x16x32_bf16 v[78:81], v[142:145], v[220:223], v[78:81]
	v_mfma_f32_16x16x32_bf16 v[74:77], v[162:165], v[220:223], v[74:77]
	v_mfma_f32_16x16x32_bf16 v[126:129], v[158:161], v[190:193], v[126:129]
	v_mfma_f32_16x16x32_bf16 v[122:125], v[166:169], v[190:193], v[122:125]
	v_mfma_f32_16x16x32_bf16 v[110:113], v[158:161], v[198:201], v[110:113]
	v_mfma_f32_16x16x32_bf16 v[106:109], v[166:169], v[198:201], v[106:109]
	v_mfma_f32_16x16x32_bf16 v[94:97], v[158:161], v[206:209], v[94:97]
	v_mfma_f32_16x16x32_bf16 v[90:93], v[166:169], v[206:209], v[90:93]
	v_mfma_f32_16x16x32_bf16 v[78:81], v[158:161], v[236:239], v[78:81]
	v_mfma_f32_16x16x32_bf16 v[74:77], v[166:169], v[236:239], v[74:77]
	v_mfma_f32_16x16x32_bf16 v[118:121], v[170:173], v[186:189], v[118:121]
	v_mfma_f32_16x16x32_bf16 v[114:117], v[178:181], v[186:189], v[114:117]
	v_mfma_f32_16x16x32_bf16 v[102:105], v[170:173], v[194:197], v[102:105]
	v_mfma_f32_16x16x32_bf16 v[98:101], v[178:181], v[194:197], v[98:101]
	v_mfma_f32_16x16x32_bf16 v[86:89], v[170:173], v[202:205], v[86:89]
	v_mfma_f32_16x16x32_bf16 v[82:85], v[178:181], v[202:205], v[82:85]
	v_mfma_f32_16x16x32_bf16 v[70:73], v[170:173], v[220:223], v[70:73]
	v_mfma_f32_16x16x32_bf16 v[66:69], v[178:181], v[220:223], v[66:69]
	v_mfma_f32_16x16x32_bf16 v[118:121], v[174:177], v[190:193], v[118:121]
	v_mfma_f32_16x16x32_bf16 v[114:117], v[182:185], v[190:193], v[114:117]
	v_mfma_f32_16x16x32_bf16 v[102:105], v[174:177], v[198:201], v[102:105]
	v_mfma_f32_16x16x32_bf16 v[98:101], v[182:185], v[198:201], v[98:101]
	v_mfma_f32_16x16x32_bf16 v[86:89], v[174:177], v[206:209], v[86:89]
	v_mfma_f32_16x16x32_bf16 v[82:85], v[182:185], v[206:209], v[82:85]
	v_mfma_f32_16x16x32_bf16 v[70:73], v[174:177], v[236:239], v[70:73]
	v_mfma_f32_16x16x32_bf16 v[66:69], v[182:185], v[236:239], v[66:69]
	s_barrier
	s_add_i32 s34, s56, s27
	v_lshl_add_u64 v[224:225], v[224:225], 0, s[96:97]
	s_mov_b32 m0, s34
	ds_read_b128 v[186:189], v157 offset:49152
	ds_read_b128 v[190:193], v157 offset:50176
	ds_read_b128 v[194:197], v157 offset:51200
	ds_read_b128 v[198:201], v157 offset:52224
	ds_read_b128 v[202:205], v157 offset:53248
	ds_read_b128 v[206:209], v157 offset:54272
	ds_read_b128 v[220:223], v157 offset:55296
	ds_read_b128 v[236:239], v157 offset:56320
	global_load_lds_dwordx4 v[224:225], off
	s_add_i32 m0, s34, 0x2000
	s_add_u32 s30, s30, 0x40080
	v_lshl_add_u64 v[224:225], v[230:231], 0, s[96:97]
	s_addc_u32 s31, s31, 0
	s_add_i32 s34, s57, s27
	global_load_lds_dwordx4 v[224:225], off
	v_lshl_add_u64 v[224:225], s[30:31], 0, v[132:133]
	s_mov_b32 m0, s34
	s_nop 0
	global_load_lds_dwordx4 v[224:225], off
	v_lshl_add_u64 v[224:225], s[30:31], 0, v[136:137]
	s_add_i32 m0, s34, 0x2000
	s_nop 0
	global_load_lds_dwordx4 v[224:225], off
	v_lshl_add_u64 v[224:225], v[240:241], 0, s[96:97]
	s_mov_b32 m0, s47
	s_nop 0
	global_load_lds_dwordx4 v[224:225], off
	v_lshl_add_u64 v[224:225], v[242:243], 0, s[96:97]
	s_mov_b32 m0, s48
	s_nop 0
	global_load_lds_dwordx4 v[224:225], off
	s_nop 0
	s_nop 0
	s_waitcnt vmcnt(8)
	s_waitcnt lgkmcnt(0)
	s_barrier
	s_waitcnt lgkmcnt(0)
	v_mfma_f32_16x16x32_bf16 v[62:65], v[142:145], v[186:189], v[62:65]
	v_mfma_f32_16x16x32_bf16 v[58:61], v[162:165], v[186:189], v[58:61]
	v_mfma_f32_16x16x32_bf16 v[46:49], v[142:145], v[194:197], v[46:49]
	v_mfma_f32_16x16x32_bf16 v[42:45], v[162:165], v[194:197], v[42:45]
	v_mfma_f32_16x16x32_bf16 v[30:33], v[142:145], v[202:205], v[30:33]
	v_mfma_f32_16x16x32_bf16 v[26:29], v[162:165], v[202:205], v[26:29]
	v_mfma_f32_16x16x32_bf16 v[14:17], v[142:145], v[220:223], v[14:17]
	v_mfma_f32_16x16x32_bf16 v[10:13], v[162:165], v[220:223], v[10:13]
	v_mfma_f32_16x16x32_bf16 v[62:65], v[158:161], v[190:193], v[62:65]
	v_mfma_f32_16x16x32_bf16 v[58:61], v[166:169], v[190:193], v[58:61]
	v_mfma_f32_16x16x32_bf16 v[46:49], v[158:161], v[198:201], v[46:49]
	v_mfma_f32_16x16x32_bf16 v[42:45], v[166:169], v[198:201], v[42:45]
	v_mfma_f32_16x16x32_bf16 v[30:33], v[158:161], v[206:209], v[30:33]
	v_mfma_f32_16x16x32_bf16 v[26:29], v[166:169], v[206:209], v[26:29]
	v_mfma_f32_16x16x32_bf16 v[14:17], v[158:161], v[236:239], v[14:17]
	v_mfma_f32_16x16x32_bf16 v[10:13], v[166:169], v[236:239], v[10:13]
	v_mfma_f32_16x16x32_bf16 v[54:57], v[170:173], v[186:189], v[54:57]
	v_mfma_f32_16x16x32_bf16 v[50:53], v[178:181], v[186:189], v[50:53]
	v_mfma_f32_16x16x32_bf16 v[38:41], v[170:173], v[194:197], v[38:41]
	v_mfma_f32_16x16x32_bf16 v[34:37], v[178:181], v[194:197], v[34:37]
	v_mfma_f32_16x16x32_bf16 v[22:25], v[170:173], v[202:205], v[22:25]
	v_mfma_f32_16x16x32_bf16 v[18:21], v[178:181], v[202:205], v[18:21]
	v_mfma_f32_16x16x32_bf16 v[6:9], v[170:173], v[220:223], v[6:9]
	v_mfma_f32_16x16x32_bf16 v[2:5], v[178:181], v[220:223], v[2:5]
	v_mfma_f32_16x16x32_bf16 v[54:57], v[174:177], v[190:193], v[54:57]
	v_mfma_f32_16x16x32_bf16 v[50:53], v[182:185], v[190:193], v[50:53]
	v_mfma_f32_16x16x32_bf16 v[38:41], v[174:177], v[198:201], v[38:41]
	v_mfma_f32_16x16x32_bf16 v[34:37], v[182:185], v[198:201], v[34:37]
	v_mfma_f32_16x16x32_bf16 v[22:25], v[174:177], v[206:209], v[22:25]
	v_mfma_f32_16x16x32_bf16 v[18:21], v[182:185], v[206:209], v[18:21]
	v_mfma_f32_16x16x32_bf16 v[6:9], v[174:177], v[236:239], v[6:9]
	v_mfma_f32_16x16x32_bf16 v[2:5], v[182:185], v[236:239], v[2:5]
	s_barrier
	s_add_i32 s55, s55, 2
	s_add_u32 s38, s38, 0x100
	s_addc_u32 s39, s39, 0
	s_add_u32 s28, s28, 0x100
	s_addc_u32 s29, s29, 0
	s_cmp_gt_u32 s55, 13
	s_cbranch_scc0 .LBB0_288
	s_and_b64 vcc, exec, s[12:13]
	s_cbranch_vccz .LBB0_291
	s_barrier

.LBB0_362:
	s_ashr_i32 s23, s22, 31
	s_lshl_b64 s[24:25], s[22:23], 19
	s_add_u32 s24, s80, s24
	s_addc_u32 s25, s81, s25
	s_and_b64 s[26:27], s[6:7], exec
	s_cselect_b32 s23, s25, s35
	s_cselect_b32 s39, s24, s34
	s_ashr_i32 s21, s20, 31
	s_lshl_b64 s[26:27], s[20:21], 19
	s_add_u32 s26, s45, s26
	s_addc_u32 s27, s46, s27
	s_and_b64 s[36:37], s[6:7], exec
	s_cselect_b32 s21, s27, s31
	s_cselect_b32 s40, s26, s30
	s_add_u32 s41, s30, 0x100
	s_addc_u32 s43, s31, 0
	s_add_u32 s30, s34, 0x40080
	s_addc_u32 s31, s35, 0
	s_mov_b32 s56, -2
	s_add_u32 s34, s30, 0xfffc0080
	s_addc_u32 s35, s31, -1
	s_add_i32 s57, 0, 0x10000
	s_cmp_eq_u32 s56, 12
	s_cselect_b32 s37, s23, s35
	s_cselect_b32 s36, s39, s34
	v_add_u32_e32 v146, s57, v155
	s_cselect_b32 s35, s21, s43
	s_cselect_b32 s34, s40, s41
	s_add_i32 s60, 0, 0x14000
	ds_read_b128 v[142:145], v146
	ds_read_b128 v[168:171], v146 offset:1024
	ds_read_b128 v[172:175], v146 offset:2048
	ds_read_b128 v[176:179], v146 offset:3072
	v_add_u32_e32 v146, s60, v155
	ds_read_b128 v[180:183], v146
	ds_read_b128 v[184:187], v146 offset:1024
	ds_read_b128 v[188:191], v146 offset:2048
	ds_read_b128 v[192:195], v146 offset:3072
	v_lshl_add_u64 v[146:147], s[30:31], 0, v[140:141]
	s_add_i32 m0, s48, 0xc000
	ds_read_b128 v[196:199], v157
	ds_read_b128 v[200:203], v157 offset:1024
	ds_read_b128 v[204:207], v157 offset:2048
	ds_read_b128 v[220:223], v157 offset:3072
	ds_read_b128 v[236:239], v157 offset:4096
	ds_read_b128 v[240:243], v157 offset:5120
	ds_read_b128 v[244:247], v157 offset:6144
	ds_read_b128 v[248:251], v157 offset:7168
	global_load_lds_dwordx4 v[146:147], off
	v_lshl_add_u64 v[146:147], s[30:31], 0, v[138:139]
	s_add_i32 m0, s48, 0xe000
	s_nop 0
	global_load_lds_dwordx4 v[146:147], off
	s_branch .Lpadj_3
	s_nop 0
	s_nop 0
	s_nop 0
	s_nop 0
	s_nop 0
.Lpadj_3:
	s_waitcnt vmcnt(8)
	s_waitcnt lgkmcnt(0)
	s_barrier
	s_waitcnt lgkmcnt(0)
	v_mfma_f32_16x16x32_bf16 v[126:129], v[142:145], v[196:199], 0
	v_mfma_f32_16x16x32_bf16 v[118:121], v[172:175], v[196:199], 0
	v_mfma_f32_16x16x32_bf16 v[110:113], v[142:145], v[204:207], 0
	v_mfma_f32_16x16x32_bf16 v[102:105], v[172:175], v[204:207], 0
	v_mfma_f32_16x16x32_bf16 v[94:97], v[142:145], v[236:239], 0
	v_mfma_f32_16x16x32_bf16 v[86:89], v[172:175], v[236:239], 0
	v_mfma_f32_16x16x32_bf16 v[78:81], v[142:145], v[244:247], 0
	v_mfma_f32_16x16x32_bf16 v[70:73], v[172:175], v[244:247], 0
	v_mfma_f32_16x16x32_bf16 v[126:129], v[168:171], v[200:203], v[126:129]
	v_mfma_f32_16x16x32_bf16 v[118:121], v[176:179], v[200:203], v[118:121]
	v_mfma_f32_16x16x32_bf16 v[110:113], v[168:171], v[220:223], v[110:113]
	v_mfma_f32_16x16x32_bf16 v[102:105], v[176:179], v[220:223], v[102:105]
	v_mfma_f32_16x16x32_bf16 v[94:97], v[168:171], v[240:243], v[94:97]
	v_mfma_f32_16x16x32_bf16 v[86:89], v[176:179], v[240:243], v[86:89]
	v_mfma_f32_16x16x32_bf16 v[78:81], v[168:171], v[248:251], v[78:81]
	v_mfma_f32_16x16x32_bf16 v[70:73], v[176:179], v[248:251], v[70:73]
	v_mfma_f32_16x16x32_bf16 v[122:125], v[180:183], v[196:199], 0
	v_mfma_f32_16x16x32_bf16 v[114:117], v[188:191], v[196:199], 0
	v_mfma_f32_16x16x32_bf16 v[106:109], v[180:183], v[204:207], 0
	v_mfma_f32_16x16x32_bf16 v[98:101], v[188:191], v[204:207], 0
	v_mfma_f32_16x16x32_bf16 v[90:93], v[180:183], v[236:239], 0
	v_mfma_f32_16x16x32_bf16 v[82:85], v[188:191], v[236:239], 0
	v_mfma_f32_16x16x32_bf16 v[74:77], v[180:183], v[244:247], 0
	v_mfma_f32_16x16x32_bf16 v[66:69], v[188:191], v[244:247], 0
	v_mfma_f32_16x16x32_bf16 v[122:125], v[184:187], v[200:203], v[122:125]
	v_mfma_f32_16x16x32_bf16 v[114:117], v[192:195], v[200:203], v[114:117]
	v_mfma_f32_16x16x32_bf16 v[106:109], v[184:187], v[220:223], v[106:109]
	v_mfma_f32_16x16x32_bf16 v[98:101], v[192:195], v[220:223], v[98:101]
	v_mfma_f32_16x16x32_bf16 v[90:93], v[184:187], v[240:243], v[90:93]
	v_mfma_f32_16x16x32_bf16 v[82:85], v[192:195], v[240:243], v[82:85]
	v_mfma_f32_16x16x32_bf16 v[74:77], v[184:187], v[248:251], v[74:77]
	v_mfma_f32_16x16x32_bf16 v[66:69], v[192:195], v[248:251], v[66:69]
	s_barrier
	s_add_i32 s57, s57, s44
	v_lshl_add_u64 v[146:147], s[34:35], 0, v[134:135]
	s_mov_b32 m0, s57
	ds_read_b128 v[196:199], v157 offset:16384
	ds_read_b128 v[200:203], v157 offset:17408
	ds_read_b128 v[204:207], v157 offset:18432
	ds_read_b128 v[220:223], v157 offset:19456
	ds_read_b128 v[236:239], v157 offset:20480
	ds_read_b128 v[240:243], v157 offset:21504
	ds_read_b128 v[244:247], v157 offset:22528
	ds_read_b128 v[248:251], v157 offset:23552
	global_load_lds_dwordx4 v[146:147], off
	s_add_i32 m0, s57, 0x2000
	s_add_u32 s58, s34, 0x40000
	v_lshl_add_u64 v[208:209], s[34:35], 0, v[130:131]
	s_addc_u32 s59, s35, 0
	s_add_i32 s57, s60, s44
	global_load_lds_dwordx4 v[208:209], off
	v_lshl_add_u64 v[224:225], s[58:59], 0, v[134:135]
	s_mov_b32 m0, s57
	v_lshl_add_u64 v[230:231], s[36:37], 0, v[132:133]
	global_load_lds_dwordx4 v[224:225], off
	v_lshl_add_u64 v[224:225], s[58:59], 0, v[130:131]
	s_add_i32 m0, s57, 0x2000
	s_nop 0
	global_load_lds_dwordx4 v[224:225], off
	v_lshl_add_u64 v[224:225], s[36:37], 0, v[136:137]
	s_mov_b32 m0, s48
	s_nop 0
	global_load_lds_dwordx4 v[224:225], off
	s_mov_b32 m0, s49
	s_nop 0
	global_load_lds_dwordx4 v[230:231], off
	s_nop 0
	s_nop 0
	s_nop 0
	s_waitcnt vmcnt(8)
	s_waitcnt lgkmcnt(0)
	s_barrier
	s_waitcnt lgkmcnt(0)
	v_mfma_f32_16x16x32_bf16 v[62:65], v[142:145], v[196:199], 0
	v_mfma_f32_16x16x32_bf16 v[54:57], v[172:175], v[196:199], 0
	v_mfma_f32_16x16x32_bf16 v[46:49], v[142:145], v[204:207], 0
	v_mfma_f32_16x16x32_bf16 v[38:41], v[172:175], v[204:207], 0
	v_mfma_f32_16x16x32_bf16 v[30:33], v[142:145], v[236:239], 0
	v_mfma_f32_16x16x32_bf16 v[22:25], v[172:175], v[236:239], 0
	v_mfma_f32_16x16x32_bf16 v[14:17], v[142:145], v[244:247], 0
	v_mfma_f32_16x16x32_bf16 v[6:9], v[172:175], v[244:247], 0
	v_mfma_f32_16x16x32_bf16 v[62:65], v[168:171], v[200:203], v[62:65]
	v_mfma_f32_16x16x32_bf16 v[54:57], v[176:179], v[200:203], v[54:57]
	v_mfma_f32_16x16x32_bf16 v[46:49], v[168:171], v[220:223], v[46:49]
	v_mfma_f32_16x16x32_bf16 v[38:41], v[176:179], v[220:223], v[38:41]
	v_mfma_f32_16x16x32_bf16 v[30:33], v[168:171], v[240:243], v[30:33]
	v_mfma_f32_16x16x32_bf16 v[22:25], v[176:179], v[240:243], v[22:25]
	v_mfma_f32_16x16x32_bf16 v[14:17], v[168:171], v[248:251], v[14:17]
	v_mfma_f32_16x16x32_bf16 v[6:9], v[176:179], v[248:251], v[6:9]
	v_mfma_f32_16x16x32_bf16 v[58:61], v[180:183], v[196:199], 0
	v_mfma_f32_16x16x32_bf16 v[50:53], v[188:191], v[196:199], 0
	v_mfma_f32_16x16x32_bf16 v[42:45], v[180:183], v[204:207], 0
	v_mfma_f32_16x16x32_bf16 v[34:37], v[188:191], v[204:207], 0
	v_mfma_f32_16x16x32_bf16 v[26:29], v[180:183], v[236:239], 0
	v_mfma_f32_16x16x32_bf16 v[18:21], v[188:191], v[236:239], 0
	v_mfma_f32_16x16x32_bf16 v[10:13], v[180:183], v[244:247], 0
	v_mfma_f32_16x16x32_bf16 v[2:5], v[188:191], v[244:247], 0
	v_mfma_f32_16x16x32_bf16 v[58:61], v[184:187], v[200:203], v[58:61]
	v_mfma_f32_16x16x32_bf16 v[50:53], v[192:195], v[200:203], v[50:53]
	v_mfma_f32_16x16x32_bf16 v[42:45], v[184:187], v[220:223], v[42:45]
	v_mfma_f32_16x16x32_bf16 v[34:37], v[192:195], v[220:223], v[34:37]
	v_mfma_f32_16x16x32_bf16 v[26:29], v[184:187], v[240:243], v[26:29]
	v_mfma_f32_16x16x32_bf16 v[18:21], v[192:195], v[240:243], v[18:21]
	v_mfma_f32_16x16x32_bf16 v[10:13], v[184:187], v[248:251], v[10:13]
	v_mfma_f32_16x16x32_bf16 v[2:5], v[192:195], v[248:251], v[2:5]
	s_barrier
	s_add_i32 s57, 0, 0x18000
	v_add_u32_e32 v164, s57, v155
	s_add_i32 s58, 0, 0x1c000
	ds_read_b128 v[142:145], v164
	ds_read_b128 v[168:171], v164 offset:1024
	ds_read_b128 v[172:175], v164 offset:2048
	ds_read_b128 v[176:179], v164 offset:3072
	v_add_u32_e32 v164, s58, v155
	ds_read_b128 v[180:183], v164
	ds_read_b128 v[184:187], v164 offset:1024
	ds_read_b128 v[188:191], v164 offset:2048
	ds_read_b128 v[192:195], v164 offset:3072
	s_add_u32 s36, s36, 0x40000
	s_addc_u32 s37, s37, 0
	s_mov_b32 m0, s50
	v_lshl_add_u64 v[252:253], s[36:37], 0, v[136:137]
	ds_read_b128 v[196:199], v157 offset:32768
	ds_read_b128 v[200:203], v157 offset:33792
	ds_read_b128 v[204:207], v157 offset:34816
	ds_read_b128 v[220:223], v157 offset:35840
	ds_read_b128 v[236:239], v157 offset:36864
	ds_read_b128 v[240:243], v157 offset:37888
	ds_read_b128 v[244:247], v157 offset:38912
	ds_read_b128 v[248:251], v157 offset:39936
	global_load_lds_dwordx4 v[252:253], off
	v_lshl_add_u64 v[252:253], s[36:37], 0, v[132:133]
	s_mov_b32 m0, s51
	s_nop 0
	global_load_lds_dwordx4 v[252:253], off
	s_branch .Lpadj_4
	s_nop 0
	s_nop 0
	s_nop 0
	s_nop 0
	s_nop 0
	s_nop 0
.Lpadj_4:
	s_waitcnt vmcnt(8)
	s_waitcnt lgkmcnt(0)
	s_barrier
	s_waitcnt lgkmcnt(0)
	v_mfma_f32_16x16x32_bf16 v[126:129], v[142:145], v[196:199], v[126:129]
	v_mfma_f32_16x16x32_bf16 v[118:121], v[172:175], v[196:199], v[118:121]
	v_mfma_f32_16x16x32_bf16 v[110:113], v[142:145], v[204:207], v[110:113]
	v_mfma_f32_16x16x32_bf16 v[102:105], v[172:175], v[204:207], v[102:105]
	v_mfma_f32_16x16x32_bf16 v[94:97], v[142:145], v[236:239], v[94:97]
	v_mfma_f32_16x16x32_bf16 v[86:89], v[172:175], v[236:239], v[86:89]
	v_mfma_f32_16x16x32_bf16 v[78:81], v[142:145], v[244:247], v[78:81]
	v_mfma_f32_16x16x32_bf16 v[70:73], v[172:175], v[244:247], v[70:73]
	v_mfma_f32_16x16x32_bf16 v[126:129], v[168:171], v[200:203], v[126:129]
	v_mfma_f32_16x16x32_bf16 v[118:121], v[176:179], v[200:203], v[118:121]
	v_mfma_f32_16x16x32_bf16 v[110:113], v[168:171], v[220:223], v[110:113]
	v_mfma_f32_16x16x32_bf16 v[102:105], v[176:179], v[220:223], v[102:105]
	v_mfma_f32_16x16x32_bf16 v[94:97], v[168:171], v[240:243], v[94:97]
	v_mfma_f32_16x16x32_bf16 v[86:89], v[176:179], v[240:243], v[86:89]
	v_mfma_f32_16x16x32_bf16 v[78:81], v[168:171], v[248:251], v[78:81]
	v_mfma_f32_16x16x32_bf16 v[70:73], v[176:179], v[248:251], v[70:73]
	v_mfma_f32_16x16x32_bf16 v[122:125], v[180:183], v[196:199], v[122:125]
	v_mfma_f32_16x16x32_bf16 v[114:117], v[188:191], v[196:199], v[114:117]
	v_mfma_f32_16x16x32_bf16 v[106:109], v[180:183], v[204:207], v[106:109]
	v_mfma_f32_16x16x32_bf16 v[98:101], v[188:191], v[204:207], v[98:101]
	v_mfma_f32_16x16x32_bf16 v[90:93], v[180:183], v[236:239], v[90:93]
	v_mfma_f32_16x16x32_bf16 v[82:85], v[188:191], v[236:239], v[82:85]
	v_mfma_f32_16x16x32_bf16 v[74:77], v[180:183], v[244:247], v[74:77]
	v_mfma_f32_16x16x32_bf16 v[66:69], v[188:191], v[244:247], v[66:69]
	v_mfma_f32_16x16x32_bf16 v[122:125], v[184:187], v[200:203], v[122:125]
	v_mfma_f32_16x16x32_bf16 v[114:117], v[192:195], v[200:203], v[114:117]
	v_mfma_f32_16x16x32_bf16 v[106:109], v[184:187], v[220:223], v[106:109]
	v_mfma_f32_16x16x32_bf16 v[98:101], v[192:195], v[220:223], v[98:101]
	v_mfma_f32_16x16x32_bf16 v[90:93], v[184:187], v[240:243], v[90:93]
	v_mfma_f32_16x16x32_bf16 v[82:85], v[192:195], v[240:243], v[82:85]
	v_mfma_f32_16x16x32_bf16 v[74:77], v[184:187], v[248:251], v[74:77]
	v_mfma_f32_16x16x32_bf16 v[66:69], v[192:195], v[248:251], v[66:69]
	s_barrier
	s_add_i32 s36, s57, s44
	v_lshl_add_u64 v[146:147], v[146:147], 0, s[96:97]
	s_mov_b32 m0, s36
	ds_read_b128 v[196:199], v157 offset:49152
	ds_read_b128 v[200:203], v157 offset:50176
	ds_read_b128 v[204:207], v157 offset:51200
	ds_read_b128 v[220:223], v157 offset:52224
	ds_read_b128 v[236:239], v157 offset:53248
	ds_read_b128 v[240:243], v157 offset:54272
	ds_read_b128 v[244:247], v157 offset:55296
	ds_read_b128 v[248:251], v157 offset:56320
	global_load_lds_dwordx4 v[146:147], off
	s_add_i32 m0, s36, 0x2000
	s_add_u32 s34, s34, 0x40080
	v_lshl_add_u64 v[146:147], v[208:209], 0, s[96:97]
	s_addc_u32 s35, s35, 0
	s_add_i32 s36, s58, s44
	global_load_lds_dwordx4 v[146:147], off
	v_lshl_add_u64 v[146:147], s[34:35], 0, v[134:135]
	s_mov_b32 m0, s36
	s_nop 0
	global_load_lds_dwordx4 v[146:147], off
	v_lshl_add_u64 v[146:147], s[34:35], 0, v[130:131]
	s_add_i32 m0, s36, 0x2000
	s_nop 0
	global_load_lds_dwordx4 v[146:147], off
	v_lshl_add_u64 v[146:147], v[224:225], 0, s[96:97]
	s_mov_b32 m0, s52
	s_nop 0
	global_load_lds_dwordx4 v[146:147], off
	v_lshl_add_u64 v[146:147], v[230:231], 0, s[96:97]
	s_mov_b32 m0, s53
	s_nop 0
	global_load_lds_dwordx4 v[146:147], off
	s_nop 0
	s_nop 0
	s_waitcnt vmcnt(8)
	s_waitcnt lgkmcnt(0)
	s_barrier
	s_waitcnt lgkmcnt(0)
	v_mfma_f32_16x16x32_bf16 v[62:65], v[142:145], v[196:199], v[62:65]
	v_mfma_f32_16x16x32_bf16 v[54:57], v[172:175], v[196:199], v[54:57]
	v_mfma_f32_16x16x32_bf16 v[46:49], v[142:145], v[204:207], v[46:49]
	v_mfma_f32_16x16x32_bf16 v[38:41], v[172:175], v[204:207], v[38:41]
	v_mfma_f32_16x16x32_bf16 v[30:33], v[142:145], v[236:239], v[30:33]
	v_mfma_f32_16x16x32_bf16 v[22:25], v[172:175], v[236:239], v[22:25]
	v_mfma_f32_16x16x32_bf16 v[14:17], v[142:145], v[244:247], v[14:17]
	v_mfma_f32_16x16x32_bf16 v[6:9], v[172:175], v[244:247], v[6:9]
	v_mfma_f32_16x16x32_bf16 v[62:65], v[168:171], v[200:203], v[62:65]
	v_mfma_f32_16x16x32_bf16 v[54:57], v[176:179], v[200:203], v[54:57]
	v_mfma_f32_16x16x32_bf16 v[46:49], v[168:171], v[220:223], v[46:49]
	v_mfma_f32_16x16x32_bf16 v[38:41], v[176:179], v[220:223], v[38:41]
	v_mfma_f32_16x16x32_bf16 v[30:33], v[168:171], v[240:243], v[30:33]
	v_mfma_f32_16x16x32_bf16 v[22:25], v[176:179], v[240:243], v[22:25]
	v_mfma_f32_16x16x32_bf16 v[14:17], v[168:171], v[248:251], v[14:17]
	v_mfma_f32_16x16x32_bf16 v[6:9], v[176:179], v[248:251], v[6:9]
	v_mfma_f32_16x16x32_bf16 v[58:61], v[180:183], v[196:199], v[58:61]
	v_mfma_f32_16x16x32_bf16 v[50:53], v[188:191], v[196:199], v[50:53]
	v_mfma_f32_16x16x32_bf16 v[42:45], v[180:183], v[204:207], v[42:45]
	v_mfma_f32_16x16x32_bf16 v[34:37], v[188:191], v[204:207], v[34:37]
	v_mfma_f32_16x16x32_bf16 v[26:29], v[180:183], v[236:239], v[26:29]
	v_mfma_f32_16x16x32_bf16 v[18:21], v[188:191], v[236:239], v[18:21]
	v_mfma_f32_16x16x32_bf16 v[10:13], v[180:183], v[244:247], v[10:13]
	v_mfma_f32_16x16x32_bf16 v[2:5], v[188:191], v[244:247], v[2:5]
	v_mfma_f32_16x16x32_bf16 v[58:61], v[184:187], v[200:203], v[58:61]
	v_mfma_f32_16x16x32_bf16 v[50:53], v[192:195], v[200:203], v[50:53]
	v_mfma_f32_16x16x32_bf16 v[42:45], v[184:187], v[220:223], v[42:45]
	v_mfma_f32_16x16x32_bf16 v[34:37], v[192:195], v[220:223], v[34:37]
	v_mfma_f32_16x16x32_bf16 v[26:29], v[184:187], v[240:243], v[26:29]
	v_mfma_f32_16x16x32_bf16 v[18:21], v[192:195], v[240:243], v[18:21]
	v_mfma_f32_16x16x32_bf16 v[10:13], v[184:187], v[248:251], v[10:13]
	v_mfma_f32_16x16x32_bf16 v[2:5], v[192:195], v[248:251], v[2:5]
	s_barrier
	s_add_i32 s56, s56, 2
	s_add_u32 s41, s41, 0x100
	s_addc_u32 s43, s43, 0
	s_add_u32 s30, s30, 0x100
	s_addc_u32 s31, s31, 0
	s_cmp_gt_u32 s56, 13
.LBB0_363:
	s_add_u32 s34, s30, 0xfffc0080
	s_addc_u32 s35, s31, -1
	s_add_i32 s57, 0, 0x10000
	s_cmp_eq_u32 s56, 12
	s_cselect_b32 s37, s23, s35
	s_cselect_b32 s36, s39, s34
	v_add_u32_e32 v146, s57, v155
	s_cselect_b32 s35, s21, s43
	s_cselect_b32 s34, s40, s41
	s_add_i32 s60, 0, 0x14000
	ds_read_b128 v[142:145], v146
	ds_read_b128 v[168:171], v146 offset:1024
	ds_read_b128 v[172:175], v146 offset:2048
	ds_read_b128 v[176:179], v146 offset:3072
	v_add_u32_e32 v146, s60, v155
	ds_read_b128 v[180:183], v146
	ds_read_b128 v[184:187], v146 offset:1024
	ds_read_b128 v[188:191], v146 offset:2048
	ds_read_b128 v[192:195], v146 offset:3072
	v_lshl_add_u64 v[146:147], s[30:31], 0, v[140:141]
	s_add_i32 m0, s48, 0xc000
	ds_read_b128 v[196:199], v157
	ds_read_b128 v[200:203], v157 offset:1024
	ds_read_b128 v[204:207], v157 offset:2048
	ds_read_b128 v[220:223], v157 offset:3072
	ds_read_b128 v[236:239], v157 offset:4096
	ds_read_b128 v[240:243], v157 offset:5120
	ds_read_b128 v[244:247], v157 offset:6144
	ds_read_b128 v[248:251], v157 offset:7168
	global_load_lds_dwordx4 v[146:147], off
	v_lshl_add_u64 v[146:147], s[30:31], 0, v[138:139]
	s_add_i32 m0, s48, 0xe000
	s_nop 0
	global_load_lds_dwordx4 v[146:147], off
	s_branch .Lpadj_5
	s_nop 0
	s_nop 0
	s_nop 0
	s_nop 0
	s_nop 0
	s_nop 0
	s_nop 0
.Lpadj_5:
	s_waitcnt vmcnt(8)
	s_waitcnt lgkmcnt(0)
	s_barrier
	s_waitcnt lgkmcnt(0)
	v_mfma_f32_16x16x32_bf16 v[126:129], v[142:145], v[196:199], v[126:129]
	v_mfma_f32_16x16x32_bf16 v[118:121], v[172:175], v[196:199], v[118:121]
	v_mfma_f32_16x16x32_bf16 v[110:113], v[142:145], v[204:207], v[110:113]
	v_mfma_f32_16x16x32_bf16 v[102:105], v[172:175], v[204:207], v[102:105]
	v_mfma_f32_16x16x32_bf16 v[94:97], v[142:145], v[236:239], v[94:97]
	v_mfma_f32_16x16x32_bf16 v[86:89], v[172:175], v[236:239], v[86:89]
	v_mfma_f32_16x16x32_bf16 v[78:81], v[142:145], v[244:247], v[78:81]
	v_mfma_f32_16x16x32_bf16 v[70:73], v[172:175], v[244:247], v[70:73]
	v_mfma_f32_16x16x32_bf16 v[126:129], v[168:171], v[200:203], v[126:129]
	v_mfma_f32_16x16x32_bf16 v[118:121], v[176:179], v[200:203], v[118:121]
	v_mfma_f32_16x16x32_bf16 v[110:113], v[168:171], v[220:223], v[110:113]
	v_mfma_f32_16x16x32_bf16 v[102:105], v[176:179], v[220:223], v[102:105]
	v_mfma_f32_16x16x32_bf16 v[94:97], v[168:171], v[240:243], v[94:97]
	v_mfma_f32_16x16x32_bf16 v[86:89], v[176:179], v[240:243], v[86:89]
	v_mfma_f32_16x16x32_bf16 v[78:81], v[168:171], v[248:251], v[78:81]
	v_mfma_f32_16x16x32_bf16 v[70:73], v[176:179], v[248:251], v[70:73]
	v_mfma_f32_16x16x32_bf16 v[122:125], v[180:183], v[196:199], v[122:125]
	v_mfma_f32_16x16x32_bf16 v[114:117], v[188:191], v[196:199], v[114:117]
	v_mfma_f32_16x16x32_bf16 v[106:109], v[180:183], v[204:207], v[106:109]
	v_mfma_f32_16x16x32_bf16 v[98:101], v[188:191], v[204:207], v[98:101]
	v_mfma_f32_16x16x32_bf16 v[90:93], v[180:183], v[236:239], v[90:93]
	v_mfma_f32_16x16x32_bf16 v[82:85], v[188:191], v[236:239], v[82:85]
	v_mfma_f32_16x16x32_bf16 v[74:77], v[180:183], v[244:247], v[74:77]
	v_mfma_f32_16x16x32_bf16 v[66:69], v[188:191], v[244:247], v[66:69]
	v_mfma_f32_16x16x32_bf16 v[122:125], v[184:187], v[200:203], v[122:125]
	v_mfma_f32_16x16x32_bf16 v[114:117], v[192:195], v[200:203], v[114:117]
	v_mfma_f32_16x16x32_bf16 v[106:109], v[184:187], v[220:223], v[106:109]
	v_mfma_f32_16x16x32_bf16 v[98:101], v[192:195], v[220:223], v[98:101]
	v_mfma_f32_16x16x32_bf16 v[90:93], v[184:187], v[240:243], v[90:93]
	v_mfma_f32_16x16x32_bf16 v[82:85], v[192:195], v[240:243], v[82:85]
	v_mfma_f32_16x16x32_bf16 v[74:77], v[184:187], v[248:251], v[74:77]
	v_mfma_f32_16x16x32_bf16 v[66:69], v[192:195], v[248:251], v[66:69]
	s_barrier
	s_add_i32 s57, s57, s44
	v_lshl_add_u64 v[146:147], s[34:35], 0, v[134:135]
	s_mov_b32 m0, s57
	ds_read_b128 v[196:199], v157 offset:16384
	ds_read_b128 v[200:203], v157 offset:17408
	ds_read_b128 v[204:207], v157 offset:18432
	ds_read_b128 v[220:223], v157 offset:19456
	ds_read_b128 v[236:239], v157 offset:20480
	ds_read_b128 v[240:243], v157 offset:21504
	ds_read_b128 v[244:247], v157 offset:22528
	ds_read_b128 v[248:251], v157 offset:23552
	global_load_lds_dwordx4 v[146:147], off
	s_add_i32 m0, s57, 0x2000
	s_add_u32 s58, s34, 0x40000
	v_lshl_add_u64 v[208:209], s[34:35], 0, v[130:131]
	s_addc_u32 s59, s35, 0
	s_add_i32 s57, s60, s44
	global_load_lds_dwordx4 v[208:209], off
	v_lshl_add_u64 v[224:225], s[58:59], 0, v[134:135]
	s_mov_b32 m0, s57
	v_lshl_add_u64 v[230:231], s[36:37], 0, v[132:133]
	global_load_lds_dwordx4 v[224:225], off
	v_lshl_add_u64 v[224:225], s[58:59], 0, v[130:131]
	s_add_i32 m0, s57, 0x2000
	s_nop 0
	global_load_lds_dwordx4 v[224:225], off
	v_lshl_add_u64 v[224:225], s[36:37], 0, v[136:137]
	s_mov_b32 m0, s48
	s_nop 0
	global_load_lds_dwordx4 v[224:225], off
	s_mov_b32 m0, s49
	s_nop 0
	global_load_lds_dwordx4 v[230:231], off
	s_nop 0
	s_nop 0
	s_nop 0
	s_waitcnt vmcnt(8)
	s_waitcnt lgkmcnt(0)
	s_barrier
	s_waitcnt lgkmcnt(0)
	v_mfma_f32_16x16x32_bf16 v[62:65], v[142:145], v[196:199], v[62:65]
	v_mfma_f32_16x16x32_bf16 v[54:57], v[172:175], v[196:199], v[54:57]
	v_mfma_f32_16x16x32_bf16 v[46:49], v[142:145], v[204:207], v[46:49]
	v_mfma_f32_16x16x32_bf16 v[38:41], v[172:175], v[204:207], v[38:41]
	v_mfma_f32_16x16x32_bf16 v[30:33], v[142:145], v[236:239], v[30:33]
	v_mfma_f32_16x16x32_bf16 v[22:25], v[172:175], v[236:239], v[22:25]
	v_mfma_f32_16x16x32_bf16 v[14:17], v[142:145], v[244:247], v[14:17]
	v_mfma_f32_16x16x32_bf16 v[6:9], v[172:175], v[244:247], v[6:9]
	v_mfma_f32_16x16x32_bf16 v[62:65], v[168:171], v[200:203], v[62:65]
	v_mfma_f32_16x16x32_bf16 v[54:57], v[176:179], v[200:203], v[54:57]
	v_mfma_f32_16x16x32_bf16 v[46:49], v[168:171], v[220:223], v[46:49]
	v_mfma_f32_16x16x32_bf16 v[38:41], v[176:179], v[220:223], v[38:41]
	v_mfma_f32_16x16x32_bf16 v[30:33], v[168:171], v[240:243], v[30:33]
	v_mfma_f32_16x16x32_bf16 v[22:25], v[176:179], v[240:243], v[22:25]
	v_mfma_f32_16x16x32_bf16 v[14:17], v[168:171], v[248:251], v[14:17]
	v_mfma_f32_16x16x32_bf16 v[6:9], v[176:179], v[248:251], v[6:9]
	v_mfma_f32_16x16x32_bf16 v[58:61], v[180:183], v[196:199], v[58:61]
	v_mfma_f32_16x16x32_bf16 v[50:53], v[188:191], v[196:199], v[50:53]
	v_mfma_f32_16x16x32_bf16 v[42:45], v[180:183], v[204:207], v[42:45]
	v_mfma_f32_16x16x32_bf16 v[34:37], v[188:191], v[204:207], v[34:37]
	v_mfma_f32_16x16x32_bf16 v[26:29], v[180:183], v[236:239], v[26:29]
	v_mfma_f32_16x16x32_bf16 v[18:21], v[188:191], v[236:239], v[18:21]
	v_mfma_f32_16x16x32_bf16 v[10:13], v[180:183], v[244:247], v[10:13]
	v_mfma_f32_16x16x32_bf16 v[2:5], v[188:191], v[244:247], v[2:5]
	v_mfma_f32_16x16x32_bf16 v[58:61], v[184:187], v[200:203], v[58:61]
	v_mfma_f32_16x16x32_bf16 v[50:53], v[192:195], v[200:203], v[50:53]
	v_mfma_f32_16x16x32_bf16 v[42:45], v[184:187], v[220:223], v[42:45]
	v_mfma_f32_16x16x32_bf16 v[34:37], v[192:195], v[220:223], v[34:37]
	v_mfma_f32_16x16x32_bf16 v[26:29], v[184:187], v[240:243], v[26:29]
	v_mfma_f32_16x16x32_bf16 v[18:21], v[192:195], v[240:243], v[18:21]
	v_mfma_f32_16x16x32_bf16 v[10:13], v[184:187], v[248:251], v[10:13]
	v_mfma_f32_16x16x32_bf16 v[2:5], v[192:195], v[248:251], v[2:5]
	s_barrier
	s_add_i32 s57, 0, 0x18000
	v_add_u32_e32 v164, s57, v155
	s_add_i32 s58, 0, 0x1c000
	ds_read_b128 v[142:145], v164
	ds_read_b128 v[168:171], v164 offset:1024
	ds_read_b128 v[172:175], v164 offset:2048
	ds_read_b128 v[176:179], v164 offset:3072
	v_add_u32_e32 v164, s58, v155
	ds_read_b128 v[180:183], v164
	ds_read_b128 v[184:187], v164 offset:1024
	ds_read_b128 v[188:191], v164 offset:2048
	ds_read_b128 v[192:195], v164 offset:3072
	s_add_u32 s36, s36, 0x40000
	s_addc_u32 s37, s37, 0
	s_mov_b32 m0, s50
	v_lshl_add_u64 v[252:253], s[36:37], 0, v[136:137]
	ds_read_b128 v[196:199], v157 offset:32768
	ds_read_b128 v[200:203], v157 offset:33792
	ds_read_b128 v[204:207], v157 offset:34816
	ds_read_b128 v[220:223], v157 offset:35840
	ds_read_b128 v[236:239], v157 offset:36864
	ds_read_b128 v[240:243], v157 offset:37888
	ds_read_b128 v[244:247], v157 offset:38912
	ds_read_b128 v[248:251], v157 offset:39936
	global_load_lds_dwordx4 v[252:253], off
	v_lshl_add_u64 v[252:253], s[36:37], 0, v[132:133]
	s_mov_b32 m0, s51
	s_nop 0
	global_load_lds_dwordx4 v[252:253], off
	s_branch .Lpadj_6
	s_nop 0
	s_nop 0
	s_nop 0
	s_nop 0
	s_nop 0
	s_nop 0
.Lpadj_6:
	s_waitcnt vmcnt(8)
	s_waitcnt lgkmcnt(0)
	s_barrier
	s_waitcnt lgkmcnt(0)
	v_mfma_f32_16x16x32_bf16 v[126:129], v[142:145], v[196:199], v[126:129]
	v_mfma_f32_16x16x32_bf16 v[118:121], v[172:175], v[196:199], v[118:121]
	v_mfma_f32_16x16x32_bf16 v[110:113], v[142:145], v[204:207], v[110:113]
	v_mfma_f32_16x16x32_bf16 v[102:105], v[172:175], v[204:207], v[102:105]
	v_mfma_f32_16x16x32_bf16 v[94:97], v[142:145], v[236:239], v[94:97]
	v_mfma_f32_16x16x32_bf16 v[86:89], v[172:175], v[236:239], v[86:89]
	v_mfma_f32_16x16x32_bf16 v[78:81], v[142:145], v[244:247], v[78:81]
	v_mfma_f32_16x16x32_bf16 v[70:73], v[172:175], v[244:247], v[70:73]
	v_mfma_f32_16x16x32_bf16 v[126:129], v[168:171], v[200:203], v[126:129]
	v_mfma_f32_16x16x32_bf16 v[118:121], v[176:179], v[200:203], v[118:121]
	v_mfma_f32_16x16x32_bf16 v[110:113], v[168:171], v[220:223], v[110:113]
	v_mfma_f32_16x16x32_bf16 v[102:105], v[176:179], v[220:223], v[102:105]
	v_mfma_f32_16x16x32_bf16 v[94:97], v[168:171], v[240:243], v[94:97]
	v_mfma_f32_16x16x32_bf16 v[86:89], v[176:179], v[240:243], v[86:89]
	v_mfma_f32_16x16x32_bf16 v[78:81], v[168:171], v[248:251], v[78:81]
	v_mfma_f32_16x16x32_bf16 v[70:73], v[176:179], v[248:251], v[70:73]
	v_mfma_f32_16x16x32_bf16 v[122:125], v[180:183], v[196:199], v[122:125]
	v_mfma_f32_16x16x32_bf16 v[114:117], v[188:191], v[196:199], v[114:117]
	v_mfma_f32_16x16x32_bf16 v[106:109], v[180:183], v[204:207], v[106:109]
	v_mfma_f32_16x16x32_bf16 v[98:101], v[188:191], v[204:207], v[98:101]
	v_mfma_f32_16x16x32_bf16 v[90:93], v[180:183], v[236:239], v[90:93]
	v_mfma_f32_16x16x32_bf16 v[82:85], v[188:191], v[236:239], v[82:85]
	v_mfma_f32_16x16x32_bf16 v[74:77], v[180:183], v[244:247], v[74:77]
	v_mfma_f32_16x16x32_bf16 v[66:69], v[188:191], v[244:247], v[66:69]
	v_mfma_f32_16x16x32_bf16 v[122:125], v[184:187], v[200:203], v[122:125]
	v_mfma_f32_16x16x32_bf16 v[114:117], v[192:195], v[200:203], v[114:117]
	v_mfma_f32_16x16x32_bf16 v[106:109], v[184:187], v[220:223], v[106:109]
	v_mfma_f32_16x16x32_bf16 v[98:101], v[192:195], v[220:223], v[98:101]
	v_mfma_f32_16x16x32_bf16 v[90:93], v[184:187], v[240:243], v[90:93]
	v_mfma_f32_16x16x32_bf16 v[82:85], v[192:195], v[240:243], v[82:85]
	v_mfma_f32_16x16x32_bf16 v[74:77], v[184:187], v[248:251], v[74:77]
	v_mfma_f32_16x16x32_bf16 v[66:69], v[192:195], v[248:251], v[66:69]
	s_barrier
	s_add_i32 s36, s57, s44
	v_lshl_add_u64 v[146:147], v[146:147], 0, s[96:97]
	s_mov_b32 m0, s36
	ds_read_b128 v[196:199], v157 offset:49152
	ds_read_b128 v[200:203], v157 offset:50176
	ds_read_b128 v[204:207], v157 offset:51200
	ds_read_b128 v[220:223], v157 offset:52224
	ds_read_b128 v[236:239], v157 offset:53248
	ds_read_b128 v[240:243], v157 offset:54272
	ds_read_b128 v[244:247], v157 offset:55296
	ds_read_b128 v[248:251], v157 offset:56320
	global_load_lds_dwordx4 v[146:147], off
	s_add_i32 m0, s36, 0x2000
	s_add_u32 s34, s34, 0x40080
	v_lshl_add_u64 v[146:147], v[208:209], 0, s[96:97]
	s_addc_u32 s35, s35, 0
	s_add_i32 s36, s58, s44
	global_load_lds_dwordx4 v[146:147], off
	v_lshl_add_u64 v[146:147], s[34:35], 0, v[134:135]
	s_mov_b32 m0, s36
	s_nop 0
	global_load_lds_dwordx4 v[146:147], off
	v_lshl_add_u64 v[146:147], s[34:35], 0, v[130:131]
	s_add_i32 m0, s36, 0x2000
	s_nop 0
	global_load_lds_dwordx4 v[146:147], off
	v_lshl_add_u64 v[146:147], v[224:225], 0, s[96:97]
	s_mov_b32 m0, s52
	s_nop 0
	global_load_lds_dwordx4 v[146:147], off
	v_lshl_add_u64 v[146:147], v[230:231], 0, s[96:97]
	s_mov_b32 m0, s53
	s_nop 0
	global_load_lds_dwordx4 v[146:147], off
	s_nop 0
	s_nop 0
	s_waitcnt vmcnt(8)
	s_waitcnt lgkmcnt(0)
	s_barrier
	s_waitcnt lgkmcnt(0)
	v_mfma_f32_16x16x32_bf16 v[62:65], v[142:145], v[196:199], v[62:65]
	v_mfma_f32_16x16x32_bf16 v[54:57], v[172:175], v[196:199], v[54:57]
	v_mfma_f32_16x16x32_bf16 v[46:49], v[142:145], v[204:207], v[46:49]
	v_mfma_f32_16x16x32_bf16 v[38:41], v[172:175], v[204:207], v[38:41]
	v_mfma_f32_16x16x32_bf16 v[30:33], v[142:145], v[236:239], v[30:33]
	v_mfma_f32_16x16x32_bf16 v[22:25], v[172:175], v[236:239], v[22:25]
	v_mfma_f32_16x16x32_bf16 v[14:17], v[142:145], v[244:247], v[14:17]
	v_mfma_f32_16x16x32_bf16 v[6:9], v[172:175], v[244:247], v[6:9]
	v_mfma_f32_16x16x32_bf16 v[62:65], v[168:171], v[200:203], v[62:65]
	v_mfma_f32_16x16x32_bf16 v[54:57], v[176:179], v[200:203], v[54:57]
	v_mfma_f32_16x16x32_bf16 v[46:49], v[168:171], v[220:223], v[46:49]
	v_mfma_f32_16x16x32_bf16 v[38:41], v[176:179], v[220:223], v[38:41]
	v_mfma_f32_16x16x32_bf16 v[30:33], v[168:171], v[240:243], v[30:33]
	v_mfma_f32_16x16x32_bf16 v[22:25], v[176:179], v[240:243], v[22:25]
	v_mfma_f32_16x16x32_bf16 v[14:17], v[168:171], v[248:251], v[14:17]
	v_mfma_f32_16x16x32_bf16 v[6:9], v[176:179], v[248:251], v[6:9]
	v_mfma_f32_16x16x32_bf16 v[58:61], v[180:183], v[196:199], v[58:61]
	v_mfma_f32_16x16x32_bf16 v[50:53], v[188:191], v[196:199], v[50:53]
	v_mfma_f32_16x16x32_bf16 v[42:45], v[180:183], v[204:207], v[42:45]
	v_mfma_f32_16x16x32_bf16 v[34:37], v[188:191], v[204:207], v[34:37]
	v_mfma_f32_16x16x32_bf16 v[26:29], v[180:183], v[236:239], v[26:29]
	v_mfma_f32_16x16x32_bf16 v[18:21], v[188:191], v[236:239], v[18:21]
	v_mfma_f32_16x16x32_bf16 v[10:13], v[180:183], v[244:247], v[10:13]
	v_mfma_f32_16x16x32_bf16 v[2:5], v[188:191], v[244:247], v[2:5]
	v_mfma_f32_16x16x32_bf16 v[58:61], v[184:187], v[200:203], v[58:61]
	v_mfma_f32_16x16x32_bf16 v[50:53], v[192:195], v[200:203], v[50:53]
	v_mfma_f32_16x16x32_bf16 v[42:45], v[184:187], v[220:223], v[42:45]
	v_mfma_f32_16x16x32_bf16 v[34:37], v[192:195], v[220:223], v[34:37]
	v_mfma_f32_16x16x32_bf16 v[26:29], v[184:187], v[240:243], v[26:29]
	v_mfma_f32_16x16x32_bf16 v[18:21], v[192:195], v[240:243], v[18:21]
	v_mfma_f32_16x16x32_bf16 v[10:13], v[184:187], v[248:251], v[10:13]
	v_mfma_f32_16x16x32_bf16 v[2:5], v[192:195], v[248:251], v[2:5]
	s_barrier
	s_add_i32 s56, s56, 2
	s_add_u32 s41, s41, 0x100
	s_addc_u32 s43, s43, 0
	s_add_u32 s30, s30, 0x100
	s_addc_u32 s31, s31, 0
	s_cmp_gt_u32 s56, 13
	s_cbranch_scc0 .LBB0_363
	s_and_b64 vcc, exec, s[16:17]
	s_cbranch_vccz .LBB0_366
	s_barrier

.LBB0_476:
	s_add_i32 s63, s31, 2
	s_add_u32 s38, s28, s36
	s_addc_u32 s39, s29, s37
	s_add_u32 s64, s26, s36
	s_addc_u32 s65, s27, s37
	s_add_i32 s66, 0, 0x10000
	s_cmp_eq_u32 s59, s31
	s_cselect_b32 s39, s9, s39
	s_cselect_b32 s38, s8, s38
	s_cselect_b32 s65, s35, s65
	s_cselect_b32 s64, s34, s64
	s_add_i32 s31, 0, 0x14000
	v_add_u32_e32 v160, s66, v146
	v_add_u32_e32 v176, s31, v146
	ds_read_b128 v[148:151], v160
	ds_read_b128 v[152:155], v160 offset:1024
	ds_read_b128 v[156:159], v160 offset:2048
	ds_read_b128 v[160:163], v160 offset:3072
	ds_read_b128 v[164:167], v176
	ds_read_b128 v[168:171], v176 offset:1024
	ds_read_b128 v[172:175], v176 offset:2048
	ds_read_b128 v[176:179], v176 offset:3072
	v_lshl_add_u64 v[208:209], s[28:29], 0, v[142:143]
	s_add_i32 m0, s51, 0xc000
	ds_read_b128 v[180:183], v147
	ds_read_b128 v[184:187], v147 offset:1024
	ds_read_b128 v[188:191], v147 offset:2048
	ds_read_b128 v[192:195], v147 offset:3072
	ds_read_b128 v[196:199], v147 offset:4096
	ds_read_b128 v[200:203], v147 offset:5120
	ds_read_b128 v[204:207], v147 offset:6144
	ds_read_b128 v[220:223], v147 offset:7168
	global_load_lds_dwordx4 v[208:209], off
	v_lshl_add_u64 v[208:209], s[28:29], 0, v[144:145]
	s_add_i32 m0, s51, 0xe000
	s_nop 0
	global_load_lds_dwordx4 v[208:209], off
	s_branch .Lpadj_7
	s_nop 0
	s_nop 0
	s_nop 0
	s_nop 0
	s_nop 0
	s_nop 0
	s_nop 0
	s_nop 0
	s_nop 0
.Lpadj_7:
	s_waitcnt vmcnt(8)
	s_waitcnt lgkmcnt(0)
	s_barrier
	s_waitcnt lgkmcnt(0)
	v_mfma_f32_16x16x32_bf16 v[126:129], v[148:151], v[180:183], v[126:129]
	v_mfma_f32_16x16x32_bf16 v[122:125], v[156:159], v[180:183], v[122:125]
	v_mfma_f32_16x16x32_bf16 v[110:113], v[148:151], v[188:191], v[110:113]
	v_mfma_f32_16x16x32_bf16 v[106:109], v[156:159], v[188:191], v[106:109]
	v_mfma_f32_16x16x32_bf16 v[94:97], v[148:151], v[196:199], v[94:97]
	v_mfma_f32_16x16x32_bf16 v[90:93], v[156:159], v[196:199], v[90:93]
	v_mfma_f32_16x16x32_bf16 v[78:81], v[148:151], v[204:207], v[78:81]
	v_mfma_f32_16x16x32_bf16 v[74:77], v[156:159], v[204:207], v[74:77]
	v_mfma_f32_16x16x32_bf16 v[126:129], v[152:155], v[184:187], v[126:129]
	v_mfma_f32_16x16x32_bf16 v[122:125], v[160:163], v[184:187], v[122:125]
	v_mfma_f32_16x16x32_bf16 v[110:113], v[152:155], v[192:195], v[110:113]
	v_mfma_f32_16x16x32_bf16 v[106:109], v[160:163], v[192:195], v[106:109]
	v_mfma_f32_16x16x32_bf16 v[94:97], v[152:155], v[200:203], v[94:97]
	v_mfma_f32_16x16x32_bf16 v[90:93], v[160:163], v[200:203], v[90:93]
	v_mfma_f32_16x16x32_bf16 v[78:81], v[152:155], v[220:223], v[78:81]
	v_mfma_f32_16x16x32_bf16 v[74:77], v[160:163], v[220:223], v[74:77]
	v_mfma_f32_16x16x32_bf16 v[118:121], v[164:167], v[180:183], v[118:121]
	v_mfma_f32_16x16x32_bf16 v[114:117], v[172:175], v[180:183], v[114:117]
	v_mfma_f32_16x16x32_bf16 v[102:105], v[164:167], v[188:191], v[102:105]
	v_mfma_f32_16x16x32_bf16 v[98:101], v[172:175], v[188:191], v[98:101]
	v_mfma_f32_16x16x32_bf16 v[86:89], v[164:167], v[196:199], v[86:89]
	v_mfma_f32_16x16x32_bf16 v[82:85], v[172:175], v[196:199], v[82:85]
	v_mfma_f32_16x16x32_bf16 v[70:73], v[164:167], v[204:207], v[70:73]
	v_mfma_f32_16x16x32_bf16 v[66:69], v[172:175], v[204:207], v[66:69]
	v_mfma_f32_16x16x32_bf16 v[118:121], v[168:171], v[184:187], v[118:121]
	v_mfma_f32_16x16x32_bf16 v[114:117], v[176:179], v[184:187], v[114:117]
	v_mfma_f32_16x16x32_bf16 v[102:105], v[168:171], v[192:195], v[102:105]
	v_mfma_f32_16x16x32_bf16 v[98:101], v[176:179], v[192:195], v[98:101]
	v_mfma_f32_16x16x32_bf16 v[86:89], v[168:171], v[200:203], v[86:89]
	v_mfma_f32_16x16x32_bf16 v[82:85], v[176:179], v[200:203], v[82:85]
	v_mfma_f32_16x16x32_bf16 v[70:73], v[168:171], v[220:223], v[70:73]
	v_mfma_f32_16x16x32_bf16 v[66:69], v[176:179], v[220:223], v[66:69]
	s_barrier
	s_add_i32 s66, s66, s47
	v_lshl_add_u64 v[208:209], s[64:65], 0, v[132:133]
	s_mov_b32 m0, s66
	ds_read_b128 v[180:183], v147 offset:16384
	ds_read_b128 v[184:187], v147 offset:17408
	ds_read_b128 v[188:191], v147 offset:18432
	ds_read_b128 v[192:195], v147 offset:19456
	ds_read_b128 v[196:199], v147 offset:20480
	ds_read_b128 v[200:203], v147 offset:21504
	ds_read_b128 v[204:207], v147 offset:22528
	ds_read_b128 v[220:223], v147 offset:23552
	global_load_lds_dwordx4 v[208:209], off
	s_add_i32 m0, s66, 0x2000
	v_lshl_add_u64 v[224:225], s[64:65], 0, v[136:137]
	s_add_u32 s64, s64, s45
	s_addc_u32 s65, s65, 0
	s_add_i32 s31, s31, s47
	global_load_lds_dwordx4 v[224:225], off
	v_lshl_add_u64 v[230:231], s[64:65], 0, v[132:133]
	s_mov_b32 m0, s31
	v_lshl_add_u64 v[236:237], s[64:65], 0, v[136:137]
	global_load_lds_dwordx4 v[230:231], off
	s_add_i32 m0, s31, 0x2000
	v_lshl_add_u64 v[238:239], s[38:39], 0, v[130:131]
	global_load_lds_dwordx4 v[236:237], off
	s_mov_b32 m0, s51
	v_lshl_add_u64 v[240:241], s[38:39], 0, v[134:135]
	global_load_lds_dwordx4 v[238:239], off
	s_mov_b32 m0, s52
	s_nop 0
	global_load_lds_dwordx4 v[240:241], off
	s_branch .Lpadj_8
	s_nop 0
	s_nop 0
	s_nop 0
	s_nop 0
	s_nop 0
.Lpadj_8:
	s_waitcnt vmcnt(8)
	s_waitcnt lgkmcnt(0)
	s_barrier
	s_waitcnt lgkmcnt(0)
	v_mfma_f32_16x16x32_bf16 v[62:65], v[148:151], v[180:183], v[62:65]
	v_mfma_f32_16x16x32_bf16 v[58:61], v[156:159], v[180:183], v[58:61]
	v_mfma_f32_16x16x32_bf16 v[46:49], v[148:151], v[188:191], v[46:49]
	v_mfma_f32_16x16x32_bf16 v[42:45], v[156:159], v[188:191], v[42:45]
	v_mfma_f32_16x16x32_bf16 v[30:33], v[148:151], v[196:199], v[30:33]
	v_mfma_f32_16x16x32_bf16 v[26:29], v[156:159], v[196:199], v[26:29]
	v_mfma_f32_16x16x32_bf16 v[14:17], v[148:151], v[204:207], v[14:17]
	v_mfma_f32_16x16x32_bf16 v[10:13], v[156:159], v[204:207], v[10:13]
	v_mfma_f32_16x16x32_bf16 v[62:65], v[152:155], v[184:187], v[62:65]
	v_mfma_f32_16x16x32_bf16 v[58:61], v[160:163], v[184:187], v[58:61]
	v_mfma_f32_16x16x32_bf16 v[46:49], v[152:155], v[192:195], v[46:49]
	v_mfma_f32_16x16x32_bf16 v[42:45], v[160:163], v[192:195], v[42:45]
	v_mfma_f32_16x16x32_bf16 v[30:33], v[152:155], v[200:203], v[30:33]
	v_mfma_f32_16x16x32_bf16 v[26:29], v[160:163], v[200:203], v[26:29]
	v_mfma_f32_16x16x32_bf16 v[14:17], v[152:155], v[220:223], v[14:17]
	v_mfma_f32_16x16x32_bf16 v[10:13], v[160:163], v[220:223], v[10:13]
	v_mfma_f32_16x16x32_bf16 v[54:57], v[164:167], v[180:183], v[54:57]
	v_mfma_f32_16x16x32_bf16 v[50:53], v[172:175], v[180:183], v[50:53]
	v_mfma_f32_16x16x32_bf16 v[38:41], v[164:167], v[188:191], v[38:41]
	v_mfma_f32_16x16x32_bf16 v[34:37], v[172:175], v[188:191], v[34:37]
	v_mfma_f32_16x16x32_bf16 v[22:25], v[164:167], v[196:199], v[22:25]
	v_mfma_f32_16x16x32_bf16 v[18:21], v[172:175], v[196:199], v[18:21]
	v_mfma_f32_16x16x32_bf16 v[6:9], v[164:167], v[204:207], v[6:9]
	v_mfma_f32_16x16x32_bf16 v[2:5], v[172:175], v[204:207], v[2:5]
	v_mfma_f32_16x16x32_bf16 v[54:57], v[168:171], v[184:187], v[54:57]
	v_mfma_f32_16x16x32_bf16 v[50:53], v[176:179], v[184:187], v[50:53]
	v_mfma_f32_16x16x32_bf16 v[38:41], v[168:171], v[192:195], v[38:41]
	v_mfma_f32_16x16x32_bf16 v[34:37], v[176:179], v[192:195], v[34:37]
	v_mfma_f32_16x16x32_bf16 v[22:25], v[168:171], v[200:203], v[22:25]
	v_mfma_f32_16x16x32_bf16 v[18:21], v[176:179], v[200:203], v[18:21]
	v_mfma_f32_16x16x32_bf16 v[6:9], v[168:171], v[220:223], v[6:9]
	v_mfma_f32_16x16x32_bf16 v[2:5], v[176:179], v[220:223], v[2:5]
	s_barrier
	s_add_i32 s31, 0, 0x18000
	s_add_i32 s64, 0, 0x1c000
	v_add_u32_e32 v160, s31, v146
	v_add_u32_e32 v176, s64, v146
	ds_read_b128 v[148:151], v160
	ds_read_b128 v[152:155], v160 offset:1024
	ds_read_b128 v[156:159], v160 offset:2048
	ds_read_b128 v[160:163], v160 offset:3072
	ds_read_b128 v[164:167], v176
	ds_read_b128 v[168:171], v176 offset:1024
	ds_read_b128 v[172:175], v176 offset:2048
	ds_read_b128 v[176:179], v176 offset:3072
	s_add_u32 s38, s38, s45
	s_addc_u32 s39, s39, 0
	s_mov_b32 m0, s53
	v_lshl_add_u64 v[242:243], s[38:39], 0, v[130:131]
	ds_read_b128 v[180:183], v147 offset:32768
	ds_read_b128 v[184:187], v147 offset:33792
	ds_read_b128 v[188:191], v147 offset:34816
	ds_read_b128 v[192:195], v147 offset:35840
	ds_read_b128 v[196:199], v147 offset:36864
	ds_read_b128 v[200:203], v147 offset:37888
	ds_read_b128 v[204:207], v147 offset:38912
	ds_read_b128 v[220:223], v147 offset:39936
	global_load_lds_dwordx4 v[242:243], off
	v_lshl_add_u64 v[242:243], s[38:39], 0, v[134:135]
	s_mov_b32 m0, s54
	s_nop 0
	global_load_lds_dwordx4 v[242:243], off
	s_branch .Lpadj_9
	s_nop 0
	s_nop 0
	s_nop 0
	s_nop 0
	s_nop 0
	s_nop 0
	s_nop 0
.Lpadj_9:
	s_waitcnt vmcnt(8)
	s_waitcnt lgkmcnt(0)
	s_barrier
	s_waitcnt lgkmcnt(0)
	v_mfma_f32_16x16x32_bf16 v[126:129], v[148:151], v[180:183], v[126:129]
	v_mfma_f32_16x16x32_bf16 v[122:125], v[156:159], v[180:183], v[122:125]
	v_mfma_f32_16x16x32_bf16 v[110:113], v[148:151], v[188:191], v[110:113]
	v_mfma_f32_16x16x32_bf16 v[106:109], v[156:159], v[188:191], v[106:109]
	v_mfma_f32_16x16x32_bf16 v[94:97], v[148:151], v[196:199], v[94:97]
	v_mfma_f32_16x16x32_bf16 v[90:93], v[156:159], v[196:199], v[90:93]
	v_mfma_f32_16x16x32_bf16 v[78:81], v[148:151], v[204:207], v[78:81]
	v_mfma_f32_16x16x32_bf16 v[74:77], v[156:159], v[204:207], v[74:77]
	v_mfma_f32_16x16x32_bf16 v[126:129], v[152:155], v[184:187], v[126:129]
	v_mfma_f32_16x16x32_bf16 v[122:125], v[160:163], v[184:187], v[122:125]
	v_mfma_f32_16x16x32_bf16 v[110:113], v[152:155], v[192:195], v[110:113]
	v_mfma_f32_16x16x32_bf16 v[106:109], v[160:163], v[192:195], v[106:109]
	v_mfma_f32_16x16x32_bf16 v[94:97], v[152:155], v[200:203], v[94:97]
	v_mfma_f32_16x16x32_bf16 v[90:93], v[160:163], v[200:203], v[90:93]
	v_mfma_f32_16x16x32_bf16 v[78:81], v[152:155], v[220:223], v[78:81]
	v_mfma_f32_16x16x32_bf16 v[74:77], v[160:163], v[220:223], v[74:77]
	v_mfma_f32_16x16x32_bf16 v[118:121], v[164:167], v[180:183], v[118:121]
	v_mfma_f32_16x16x32_bf16 v[114:117], v[172:175], v[180:183], v[114:117]
	v_mfma_f32_16x16x32_bf16 v[102:105], v[164:167], v[188:191], v[102:105]
	v_mfma_f32_16x16x32_bf16 v[98:101], v[172:175], v[188:191], v[98:101]
	v_mfma_f32_16x16x32_bf16 v[86:89], v[164:167], v[196:199], v[86:89]
	v_mfma_f32_16x16x32_bf16 v[82:85], v[172:175], v[196:199], v[82:85]
	v_mfma_f32_16x16x32_bf16 v[70:73], v[164:167], v[204:207], v[70:73]
	v_mfma_f32_16x16x32_bf16 v[66:69], v[172:175], v[204:207], v[66:69]
	v_mfma_f32_16x16x32_bf16 v[118:121], v[168:171], v[184:187], v[118:121]
	v_mfma_f32_16x16x32_bf16 v[114:117], v[176:179], v[184:187], v[114:117]
	v_mfma_f32_16x16x32_bf16 v[102:105], v[168:171], v[192:195], v[102:105]
	v_mfma_f32_16x16x32_bf16 v[98:101], v[176:179], v[192:195], v[98:101]
	v_mfma_f32_16x16x32_bf16 v[86:89], v[168:171], v[200:203], v[86:89]
	v_mfma_f32_16x16x32_bf16 v[82:85], v[176:179], v[200:203], v[82:85]
	v_mfma_f32_16x16x32_bf16 v[70:73], v[168:171], v[220:223], v[70:73]
	v_mfma_f32_16x16x32_bf16 v[66:69], v[176:179], v[220:223], v[66:69]
	s_barrier
	s_add_i32 s31, s31, s47
	v_lshl_add_u64 v[208:209], v[208:209], 0, s[96:97]
	s_mov_b32 m0, s31
	ds_read_b128 v[180:183], v147 offset:49152
	ds_read_b128 v[184:187], v147 offset:50176
	ds_read_b128 v[188:191], v147 offset:51200
	ds_read_b128 v[192:195], v147 offset:52224
	ds_read_b128 v[196:199], v147 offset:53248
	ds_read_b128 v[200:203], v147 offset:54272
	ds_read_b128 v[204:207], v147 offset:55296
	ds_read_b128 v[220:223], v147 offset:56320
	global_load_lds_dwordx4 v[208:209], off
	v_lshl_add_u64 v[208:209], v[224:225], 0, s[96:97]
	s_add_i32 m0, s31, 0x2000
	s_add_i32 s31, s64, s47
	global_load_lds_dwordx4 v[208:209], off
	v_lshl_add_u64 v[208:209], v[230:231], 0, s[96:97]
	s_mov_b32 m0, s31
	s_nop 0
	global_load_lds_dwordx4 v[208:209], off
	v_lshl_add_u64 v[208:209], v[236:237], 0, s[96:97]
	s_add_i32 m0, s31, 0x2000
	s_nop 0
	global_load_lds_dwordx4 v[208:209], off
	v_lshl_add_u64 v[208:209], v[238:239], 0, s[96:97]
	s_mov_b32 m0, s57
	s_nop 0
	global_load_lds_dwordx4 v[208:209], off
	v_lshl_add_u64 v[208:209], v[240:241], 0, s[96:97]
	s_mov_b32 m0, s58
	s_nop 0
	global_load_lds_dwordx4 v[208:209], off
	s_branch .Lpadj_10
	s_nop 0
	s_nop 0
	s_nop 0
	s_nop 0
.Lpadj_10:
	s_waitcnt vmcnt(8)
	s_waitcnt lgkmcnt(0)
	s_barrier
	s_waitcnt lgkmcnt(0)
	v_mfma_f32_16x16x32_bf16 v[62:65], v[148:151], v[180:183], v[62:65]
	v_mfma_f32_16x16x32_bf16 v[58:61], v[156:159], v[180:183], v[58:61]
	v_mfma_f32_16x16x32_bf16 v[46:49], v[148:151], v[188:191], v[46:49]
	v_mfma_f32_16x16x32_bf16 v[42:45], v[156:159], v[188:191], v[42:45]
	v_mfma_f32_16x16x32_bf16 v[30:33], v[148:151], v[196:199], v[30:33]
	v_mfma_f32_16x16x32_bf16 v[26:29], v[156:159], v[196:199], v[26:29]
	v_mfma_f32_16x16x32_bf16 v[14:17], v[148:151], v[204:207], v[14:17]
	v_mfma_f32_16x16x32_bf16 v[10:13], v[156:159], v[204:207], v[10:13]
	v_mfma_f32_16x16x32_bf16 v[62:65], v[152:155], v[184:187], v[62:65]
	v_mfma_f32_16x16x32_bf16 v[58:61], v[160:163], v[184:187], v[58:61]
	v_mfma_f32_16x16x32_bf16 v[46:49], v[152:155], v[192:195], v[46:49]
	v_mfma_f32_16x16x32_bf16 v[42:45], v[160:163], v[192:195], v[42:45]
	v_mfma_f32_16x16x32_bf16 v[30:33], v[152:155], v[200:203], v[30:33]
	v_mfma_f32_16x16x32_bf16 v[26:29], v[160:163], v[200:203], v[26:29]
	v_mfma_f32_16x16x32_bf16 v[14:17], v[152:155], v[220:223], v[14:17]
	v_mfma_f32_16x16x32_bf16 v[10:13], v[160:163], v[220:223], v[10:13]
	v_mfma_f32_16x16x32_bf16 v[54:57], v[164:167], v[180:183], v[54:57]
	v_mfma_f32_16x16x32_bf16 v[50:53], v[172:175], v[180:183], v[50:53]
	v_mfma_f32_16x16x32_bf16 v[38:41], v[164:167], v[188:191], v[38:41]
	v_mfma_f32_16x16x32_bf16 v[34:37], v[172:175], v[188:191], v[34:37]
	v_mfma_f32_16x16x32_bf16 v[22:25], v[164:167], v[196:199], v[22:25]
	v_mfma_f32_16x16x32_bf16 v[18:21], v[172:175], v[196:199], v[18:21]
	v_mfma_f32_16x16x32_bf16 v[6:9], v[164:167], v[204:207], v[6:9]
	v_mfma_f32_16x16x32_bf16 v[2:5], v[172:175], v[204:207], v[2:5]
	v_mfma_f32_16x16x32_bf16 v[54:57], v[168:171], v[184:187], v[54:57]
	v_mfma_f32_16x16x32_bf16 v[50:53], v[176:179], v[184:187], v[50:53]
	v_mfma_f32_16x16x32_bf16 v[38:41], v[168:171], v[192:195], v[38:41]
	v_mfma_f32_16x16x32_bf16 v[34:37], v[176:179], v[192:195], v[34:37]
	v_mfma_f32_16x16x32_bf16 v[22:25], v[168:171], v[200:203], v[22:25]
	v_mfma_f32_16x16x32_bf16 v[18:21], v[176:179], v[200:203], v[18:21]
	v_mfma_f32_16x16x32_bf16 v[6:9], v[168:171], v[220:223], v[6:9]
	v_mfma_f32_16x16x32_bf16 v[2:5], v[176:179], v[220:223], v[2:5]
	s_barrier
	s_add_u32 s36, s36, 0x100
	s_addc_u32 s37, s37, 0
	v_lshl_add_u64 v[144:145], v[144:145], 0, s[2:3]
	v_lshl_add_u64 v[142:143], v[142:143], 0, s[2:3]
	s_cmp_ge_u32 s63, s56
	s_mov_b32 s31, s63
	s_cbranch_scc0 .LBB0_476
	s_and_b64 vcc, exec, s[6:7]
	s_cbranch_vccnz .LBB0_464
	v_mov_b32_e32 v2, 0
	s_mov_b32 s55, s61
	s_mov_b32 s50, s62
	s_mov_b64 s[26:27], s[34:35]
	s_mov_b64 s[28:29], s[8:9]
	s_mov_b32 s60, s30
	v_mov_b32_e32 v3, v2
	v_mov_b32_e32 v4, v2
	v_mov_b32_e32 v5, v2
	v_mov_b32_e32 v6, v2
	v_mov_b32_e32 v7, v2
	v_mov_b32_e32 v8, v2
	v_mov_b32_e32 v9, v2
	v_mov_b32_e32 v18, v2
	v_mov_b32_e32 v19, v2
	v_mov_b32_e32 v20, v2
	v_mov_b32_e32 v21, v2
	v_mov_b32_e32 v22, v2
	v_mov_b32_e32 v23, v2
	v_mov_b32_e32 v24, v2
	v_mov_b32_e32 v25, v2
	v_mov_b32_e32 v34, v2
	v_mov_b32_e32 v35, v2
	v_mov_b32_e32 v36, v2
	v_mov_b32_e32 v37, v2
	v_mov_b32_e32 v38, v2
	v_mov_b32_e32 v39, v2
	v_mov_b32_e32 v40, v2
	v_mov_b32_e32 v41, v2
	v_mov_b32_e32 v50, v2
	v_mov_b32_e32 v51, v2
	v_mov_b32_e32 v52, v2
	v_mov_b32_e32 v53, v2
	v_mov_b32_e32 v54, v2
	v_mov_b32_e32 v55, v2
	v_mov_b32_e32 v56, v2
	v_mov_b32_e32 v57, v2
	v_mov_b32_e32 v10, v2
	v_mov_b32_e32 v11, v2
	v_mov_b32_e32 v12, v2
	v_mov_b32_e32 v13, v2
	v_mov_b32_e32 v14, v2
	v_mov_b32_e32 v15, v2
	v_mov_b32_e32 v16, v2
	v_mov_b32_e32 v17, v2
	v_mov_b32_e32 v26, v2
	v_mov_b32_e32 v27, v2
	v_mov_b32_e32 v28, v2
	v_mov_b32_e32 v29, v2
	v_mov_b32_e32 v30, v2
	v_mov_b32_e32 v31, v2
	v_mov_b32_e32 v32, v2
	v_mov_b32_e32 v33, v2
	v_mov_b32_e32 v42, v2
	v_mov_b32_e32 v43, v2
	v_mov_b32_e32 v44, v2
	v_mov_b32_e32 v45, v2
	v_mov_b32_e32 v46, v2
	v_mov_b32_e32 v47, v2
	v_mov_b32_e32 v48, v2
	v_mov_b32_e32 v49, v2
	v_mov_b32_e32 v58, v2
	v_mov_b32_e32 v59, v2
	v_mov_b32_e32 v60, v2
	v_mov_b32_e32 v61, v2
	v_mov_b32_e32 v62, v2
	v_mov_b32_e32 v63, v2
	v_mov_b32_e32 v64, v2
	v_mov_b32_e32 v65, v2
	v_mov_b32_e32 v66, v2
	v_mov_b32_e32 v67, v2
	v_mov_b32_e32 v68, v2
	v_mov_b32_e32 v69, v2
	v_mov_b32_e32 v70, v2
	v_mov_b32_e32 v71, v2
	v_mov_b32_e32 v72, v2
	v_mov_b32_e32 v73, v2
	v_mov_b32_e32 v82, v2
	v_mov_b32_e32 v83, v2
	v_mov_b32_e32 v84, v2
	v_mov_b32_e32 v85, v2
	v_mov_b32_e32 v86, v2
	v_mov_b32_e32 v87, v2
	v_mov_b32_e32 v88, v2
	v_mov_b32_e32 v89, v2
	v_mov_b32_e32 v98, v2
	v_mov_b32_e32 v99, v2
	v_mov_b32_e32 v100, v2
	v_mov_b32_e32 v101, v2
	v_mov_b32_e32 v102, v2
	v_mov_b32_e32 v103, v2
	v_mov_b32_e32 v104, v2
	v_mov_b32_e32 v105, v2
	v_mov_b32_e32 v114, v2
	v_mov_b32_e32 v115, v2
	v_mov_b32_e32 v116, v2
	v_mov_b32_e32 v117, v2
	v_mov_b32_e32 v118, v2
	v_mov_b32_e32 v119, v2
	v_mov_b32_e32 v120, v2
	v_mov_b32_e32 v121, v2
	v_mov_b32_e32 v74, v2
	v_mov_b32_e32 v75, v2
	v_mov_b32_e32 v76, v2
	v_mov_b32_e32 v77, v2
	v_mov_b32_e32 v78, v2
	v_mov_b32_e32 v79, v2
	v_mov_b32_e32 v80, v2
	v_mov_b32_e32 v81, v2
	v_mov_b32_e32 v90, v2
	v_mov_b32_e32 v91, v2
	v_mov_b32_e32 v92, v2
	v_mov_b32_e32 v93, v2
	v_mov_b32_e32 v94, v2
	v_mov_b32_e32 v95, v2
	v_mov_b32_e32 v96, v2
	v_mov_b32_e32 v97, v2
	v_mov_b32_e32 v106, v2
	v_mov_b32_e32 v107, v2
	v_mov_b32_e32 v108, v2
	v_mov_b32_e32 v109, v2
	v_mov_b32_e32 v110, v2
	v_mov_b32_e32 v111, v2
	v_mov_b32_e32 v112, v2
	v_mov_b32_e32 v113, v2
	v_mov_b32_e32 v122, v2
	v_mov_b32_e32 v123, v2
	v_mov_b32_e32 v124, v2
	v_mov_b32_e32 v125, v2
	v_mov_b32_e32 v126, v2
	v_mov_b32_e32 v127, v2
	v_mov_b32_e32 v128, v2
	v_mov_b32_e32 v129, v2
	s_branch .LBB0_464

.LBB0_639:
	s_ashr_i32 s13, s12, 31
	s_lshl_b64 s[14:15], s[12:13], 19
	s_add_u32 s14, s80, s14
	s_addc_u32 s15, s81, s15
	s_and_b64 s[16:17], s[4:5], exec
	s_cselect_b32 s13, s15, s23
	s_cselect_b32 s19, s14, s22
	s_ashr_i32 s11, s10, 31
	s_lshl_b64 s[16:17], s[10:11], 19
	s_add_u32 s16, s26, s16
	s_addc_u32 s17, s27, s17
	s_and_b64 s[24:25], s[4:5], exec
	s_cselect_b32 s11, s17, s21
	s_cselect_b32 s41, s16, s20
	s_add_u32 s43, s20, 0x100
	s_addc_u32 s44, s21, 0
	s_add_u32 s20, s22, 0x40080
	s_addc_u32 s21, s23, 0
	s_mov_b32 s45, -2
	s_add_u32 s22, s20, 0xfffc0080
	s_addc_u32 s23, s21, -1
	s_add_i32 s46, 0, 0x10000
	s_cmp_eq_u32 s45, 12
	s_cselect_b32 s25, s13, s23
	s_cselect_b32 s24, s19, s22
	v_add_u32_e32 v150, s46, v159
	s_cselect_b32 s23, s11, s44
	s_cselect_b32 s22, s41, s43
	s_add_i32 s48, 0, 0x14000
	ds_read_b128 v[164:167], v150
	ds_read_b128 v[168:171], v150 offset:1024
	ds_read_b128 v[172:175], v150 offset:2048
	ds_read_b128 v[176:179], v150 offset:3072
	v_add_u32_e32 v150, s48, v159
	ds_read_b128 v[180:183], v150
	ds_read_b128 v[184:187], v150 offset:1024
	ds_read_b128 v[188:191], v150 offset:2048
	ds_read_b128 v[192:195], v150 offset:3072
	v_lshl_add_u64 v[150:151], s[20:21], 0, v[140:141]
	s_add_i32 m0, s30, 0xc000
	ds_read_b128 v[196:199], v162
	ds_read_b128 v[200:203], v162 offset:1024
	ds_read_b128 v[204:207], v162 offset:2048
	ds_read_b128 v[220:223], v162 offset:3072
	ds_read_b128 v[236:239], v162 offset:4096
	ds_read_b128 v[240:243], v162 offset:5120
	ds_read_b128 v[244:247], v162 offset:6144
	ds_read_b128 v[248:251], v162 offset:7168
	global_load_lds_dwordx4 v[150:151], off
	v_lshl_add_u64 v[150:151], s[20:21], 0, v[138:139]
	s_add_i32 m0, s30, 0xe000
	s_nop 0
	global_load_lds_dwordx4 v[150:151], off
	s_branch .Lpadj_11
	s_nop 0
	s_nop 0
	s_nop 0
	s_nop 0
	s_nop 0
	s_nop 0
	s_nop 0
.Lpadj_11:
	s_waitcnt vmcnt(8)
	s_waitcnt lgkmcnt(0)
	s_barrier
	s_waitcnt lgkmcnt(0)
	v_mfma_f32_16x16x32_bf16 v[126:129], v[164:167], v[196:199], 0
	v_mfma_f32_16x16x32_bf16 v[122:125], v[172:175], v[196:199], 0
	v_mfma_f32_16x16x32_bf16 v[118:121], v[164:167], v[204:207], 0
	v_mfma_f32_16x16x32_bf16 v[114:117], v[172:175], v[204:207], 0
	v_mfma_f32_16x16x32_bf16 v[110:113], v[164:167], v[236:239], 0
	v_mfma_f32_16x16x32_bf16 v[106:109], v[172:175], v[236:239], 0
	v_mfma_f32_16x16x32_bf16 v[102:105], v[164:167], v[244:247], 0
	v_mfma_f32_16x16x32_bf16 v[98:101], v[172:175], v[244:247], 0
	v_mfma_f32_16x16x32_bf16 v[126:129], v[168:171], v[200:203], v[126:129]
	v_mfma_f32_16x16x32_bf16 v[122:125], v[176:179], v[200:203], v[122:125]
	v_mfma_f32_16x16x32_bf16 v[118:121], v[168:171], v[220:223], v[118:121]
	v_mfma_f32_16x16x32_bf16 v[114:117], v[176:179], v[220:223], v[114:117]
	v_mfma_f32_16x16x32_bf16 v[110:113], v[168:171], v[240:243], v[110:113]
	v_mfma_f32_16x16x32_bf16 v[106:109], v[176:179], v[240:243], v[106:109]
	v_mfma_f32_16x16x32_bf16 v[102:105], v[168:171], v[248:251], v[102:105]
	v_mfma_f32_16x16x32_bf16 v[98:101], v[176:179], v[248:251], v[98:101]
	v_mfma_f32_16x16x32_bf16 v[94:97], v[180:183], v[196:199], 0
	v_mfma_f32_16x16x32_bf16 v[90:93], v[188:191], v[196:199], 0
	v_mfma_f32_16x16x32_bf16 v[86:89], v[180:183], v[204:207], 0
	v_mfma_f32_16x16x32_bf16 v[82:85], v[188:191], v[204:207], 0
	v_mfma_f32_16x16x32_bf16 v[78:81], v[180:183], v[236:239], 0
	v_mfma_f32_16x16x32_bf16 v[74:77], v[188:191], v[236:239], 0
	v_mfma_f32_16x16x32_bf16 v[70:73], v[180:183], v[244:247], 0
	v_mfma_f32_16x16x32_bf16 v[66:69], v[188:191], v[244:247], 0
	v_mfma_f32_16x16x32_bf16 v[94:97], v[184:187], v[200:203], v[94:97]
	v_mfma_f32_16x16x32_bf16 v[90:93], v[192:195], v[200:203], v[90:93]
	v_mfma_f32_16x16x32_bf16 v[86:89], v[184:187], v[220:223], v[86:89]
	v_mfma_f32_16x16x32_bf16 v[82:85], v[192:195], v[220:223], v[82:85]
	v_mfma_f32_16x16x32_bf16 v[78:81], v[184:187], v[240:243], v[78:81]
	v_mfma_f32_16x16x32_bf16 v[74:77], v[192:195], v[240:243], v[74:77]
	v_mfma_f32_16x16x32_bf16 v[70:73], v[184:187], v[248:251], v[70:73]
	v_mfma_f32_16x16x32_bf16 v[66:69], v[192:195], v[248:251], v[66:69]
	s_barrier
	s_add_i32 s46, s46, s28
	v_lshl_add_u64 v[150:151], s[22:23], 0, v[134:135]
	s_mov_b32 m0, s46
	ds_read_b128 v[196:199], v162 offset:16384
	ds_read_b128 v[200:203], v162 offset:17408
	ds_read_b128 v[204:207], v162 offset:18432
	ds_read_b128 v[220:223], v162 offset:19456
	ds_read_b128 v[236:239], v162 offset:20480
	ds_read_b128 v[240:243], v162 offset:21504
	ds_read_b128 v[244:247], v162 offset:22528
	ds_read_b128 v[248:251], v162 offset:23552
	global_load_lds_dwordx4 v[150:151], off
	s_add_i32 m0, s46, 0x2000
	s_add_u32 s46, s22, 0x40000
	v_lshl_add_u64 v[208:209], s[22:23], 0, v[130:131]
	s_addc_u32 s47, s23, 0
	s_add_i32 s48, s48, s28
	global_load_lds_dwordx4 v[208:209], off
	v_lshl_add_u64 v[224:225], s[46:47], 0, v[134:135]
	s_mov_b32 m0, s48
	v_lshl_add_u64 v[252:253], s[24:25], 0, v[132:133]
	global_load_lds_dwordx4 v[224:225], off
	v_lshl_add_u64 v[224:225], s[46:47], 0, v[130:131]
	s_add_i32 m0, s48, 0x2000
	s_nop 0
	global_load_lds_dwordx4 v[224:225], off
	v_lshl_add_u64 v[224:225], s[24:25], 0, v[136:137]
	s_mov_b32 m0, s30
	s_nop 0
	global_load_lds_dwordx4 v[224:225], off
	s_mov_b32 m0, s31
	s_nop 0
	global_load_lds_dwordx4 v[252:253], off
	s_nop 0
	s_nop 0
	s_nop 0
	s_waitcnt vmcnt(8)
	s_waitcnt lgkmcnt(0)
	s_barrier
	s_waitcnt lgkmcnt(0)
	v_mfma_f32_16x16x32_bf16 v[62:65], v[164:167], v[196:199], 0
	v_mfma_f32_16x16x32_bf16 v[58:61], v[172:175], v[196:199], 0
	v_mfma_f32_16x16x32_bf16 v[54:57], v[164:167], v[204:207], 0
	v_mfma_f32_16x16x32_bf16 v[50:53], v[172:175], v[204:207], 0
	v_mfma_f32_16x16x32_bf16 v[46:49], v[164:167], v[236:239], 0
	v_mfma_f32_16x16x32_bf16 v[42:45], v[172:175], v[236:239], 0
	v_mfma_f32_16x16x32_bf16 v[38:41], v[164:167], v[244:247], 0
	v_mfma_f32_16x16x32_bf16 v[34:37], v[172:175], v[244:247], 0
	v_mfma_f32_16x16x32_bf16 v[62:65], v[168:171], v[200:203], v[62:65]
	v_mfma_f32_16x16x32_bf16 v[58:61], v[176:179], v[200:203], v[58:61]
	v_mfma_f32_16x16x32_bf16 v[54:57], v[168:171], v[220:223], v[54:57]
	v_mfma_f32_16x16x32_bf16 v[50:53], v[176:179], v[220:223], v[50:53]
	v_mfma_f32_16x16x32_bf16 v[46:49], v[168:171], v[240:243], v[46:49]
	v_mfma_f32_16x16x32_bf16 v[42:45], v[176:179], v[240:243], v[42:45]
	v_mfma_f32_16x16x32_bf16 v[38:41], v[168:171], v[248:251], v[38:41]
	v_mfma_f32_16x16x32_bf16 v[34:37], v[176:179], v[248:251], v[34:37]
	v_mfma_f32_16x16x32_bf16 v[30:33], v[180:183], v[196:199], 0
	v_mfma_f32_16x16x32_bf16 v[26:29], v[188:191], v[196:199], 0
	v_mfma_f32_16x16x32_bf16 v[22:25], v[180:183], v[204:207], 0
	v_mfma_f32_16x16x32_bf16 v[18:21], v[188:191], v[204:207], 0
	v_mfma_f32_16x16x32_bf16 v[14:17], v[180:183], v[236:239], 0
	v_mfma_f32_16x16x32_bf16 v[10:13], v[188:191], v[236:239], 0
	v_mfma_f32_16x16x32_bf16 v[6:9], v[180:183], v[244:247], 0
	v_mfma_f32_16x16x32_bf16 v[2:5], v[188:191], v[244:247], 0
	v_mfma_f32_16x16x32_bf16 v[30:33], v[184:187], v[200:203], v[30:33]
	v_mfma_f32_16x16x32_bf16 v[26:29], v[192:195], v[200:203], v[26:29]
	v_mfma_f32_16x16x32_bf16 v[22:25], v[184:187], v[220:223], v[22:25]
	v_mfma_f32_16x16x32_bf16 v[18:21], v[192:195], v[220:223], v[18:21]
	v_mfma_f32_16x16x32_bf16 v[14:17], v[184:187], v[240:243], v[14:17]
	v_mfma_f32_16x16x32_bf16 v[10:13], v[192:195], v[240:243], v[10:13]
	v_mfma_f32_16x16x32_bf16 v[6:9], v[184:187], v[248:251], v[6:9]
	v_mfma_f32_16x16x32_bf16 v[2:5], v[192:195], v[248:251], v[2:5]
	s_barrier
	s_add_i32 s46, 0, 0x18000
	v_add_u32_e32 v163, s46, v159
	s_add_i32 s47, 0, 0x1c000
	ds_read_b128 v[164:167], v163
	ds_read_b128 v[168:171], v163 offset:1024
	ds_read_b128 v[172:175], v163 offset:2048
	ds_read_b128 v[176:179], v163 offset:3072
	v_add_u32_e32 v163, s47, v159
	ds_read_b128 v[180:183], v163
	ds_read_b128 v[184:187], v163 offset:1024
	ds_read_b128 v[188:191], v163 offset:2048
	ds_read_b128 v[192:195], v163 offset:3072
	s_add_u32 s24, s24, 0x40000
	s_addc_u32 s25, s25, 0
	s_mov_b32 m0, s34
	v_lshl_add_u64 v[230:231], s[24:25], 0, v[136:137]
	ds_read_b128 v[196:199], v162 offset:32768
	ds_read_b128 v[200:203], v162 offset:33792
	ds_read_b128 v[204:207], v162 offset:34816
	ds_read_b128 v[220:223], v162 offset:35840
	ds_read_b128 v[236:239], v162 offset:36864
	ds_read_b128 v[240:243], v162 offset:37888
	ds_read_b128 v[244:247], v162 offset:38912
	ds_read_b128 v[248:251], v162 offset:39936
	global_load_lds_dwordx4 v[230:231], off
	v_lshl_add_u64 v[230:231], s[24:25], 0, v[132:133]
	s_mov_b32 m0, s35
	s_nop 0
	global_load_lds_dwordx4 v[230:231], off
	s_branch .Lpadj_12
	s_nop 0
	s_nop 0
	s_nop 0
	s_nop 0
	s_nop 0
	s_nop 0
.Lpadj_12:
	s_waitcnt vmcnt(8)
	s_waitcnt lgkmcnt(0)
	s_barrier
	s_waitcnt lgkmcnt(0)
	v_mfma_f32_16x16x32_bf16 v[126:129], v[164:167], v[196:199], v[126:129]
	v_mfma_f32_16x16x32_bf16 v[122:125], v[172:175], v[196:199], v[122:125]
	v_mfma_f32_16x16x32_bf16 v[118:121], v[164:167], v[204:207], v[118:121]
	v_mfma_f32_16x16x32_bf16 v[114:117], v[172:175], v[204:207], v[114:117]
	v_mfma_f32_16x16x32_bf16 v[110:113], v[164:167], v[236:239], v[110:113]
	v_mfma_f32_16x16x32_bf16 v[106:109], v[172:175], v[236:239], v[106:109]
	v_mfma_f32_16x16x32_bf16 v[102:105], v[164:167], v[244:247], v[102:105]
	v_mfma_f32_16x16x32_bf16 v[98:101], v[172:175], v[244:247], v[98:101]
	v_mfma_f32_16x16x32_bf16 v[126:129], v[168:171], v[200:203], v[126:129]
	v_mfma_f32_16x16x32_bf16 v[122:125], v[176:179], v[200:203], v[122:125]
	v_mfma_f32_16x16x32_bf16 v[118:121], v[168:171], v[220:223], v[118:121]
	v_mfma_f32_16x16x32_bf16 v[114:117], v[176:179], v[220:223], v[114:117]
	v_mfma_f32_16x16x32_bf16 v[110:113], v[168:171], v[240:243], v[110:113]
	v_mfma_f32_16x16x32_bf16 v[106:109], v[176:179], v[240:243], v[106:109]
	v_mfma_f32_16x16x32_bf16 v[102:105], v[168:171], v[248:251], v[102:105]
	v_mfma_f32_16x16x32_bf16 v[98:101], v[176:179], v[248:251], v[98:101]
	v_mfma_f32_16x16x32_bf16 v[94:97], v[180:183], v[196:199], v[94:97]
	v_mfma_f32_16x16x32_bf16 v[90:93], v[188:191], v[196:199], v[90:93]
	v_mfma_f32_16x16x32_bf16 v[86:89], v[180:183], v[204:207], v[86:89]
	v_mfma_f32_16x16x32_bf16 v[82:85], v[188:191], v[204:207], v[82:85]
	v_mfma_f32_16x16x32_bf16 v[78:81], v[180:183], v[236:239], v[78:81]
	v_mfma_f32_16x16x32_bf16 v[74:77], v[188:191], v[236:239], v[74:77]
	v_mfma_f32_16x16x32_bf16 v[70:73], v[180:183], v[244:247], v[70:73]
	v_mfma_f32_16x16x32_bf16 v[66:69], v[188:191], v[244:247], v[66:69]
	v_mfma_f32_16x16x32_bf16 v[94:97], v[184:187], v[200:203], v[94:97]
	v_mfma_f32_16x16x32_bf16 v[90:93], v[192:195], v[200:203], v[90:93]
	v_mfma_f32_16x16x32_bf16 v[86:89], v[184:187], v[220:223], v[86:89]
	v_mfma_f32_16x16x32_bf16 v[82:85], v[192:195], v[220:223], v[82:85]
	v_mfma_f32_16x16x32_bf16 v[78:81], v[184:187], v[240:243], v[78:81]
	v_mfma_f32_16x16x32_bf16 v[74:77], v[192:195], v[240:243], v[74:77]
	v_mfma_f32_16x16x32_bf16 v[70:73], v[184:187], v[248:251], v[70:73]
	v_mfma_f32_16x16x32_bf16 v[66:69], v[192:195], v[248:251], v[66:69]
	s_barrier
	s_add_i32 s24, s46, s28
	v_lshl_add_u64 v[150:151], v[150:151], 0, s[96:97]
	s_mov_b32 m0, s24
	ds_read_b128 v[196:199], v162 offset:49152
	ds_read_b128 v[200:203], v162 offset:50176
	ds_read_b128 v[204:207], v162 offset:51200
	ds_read_b128 v[220:223], v162 offset:52224
	ds_read_b128 v[236:239], v162 offset:53248
	ds_read_b128 v[240:243], v162 offset:54272
	ds_read_b128 v[244:247], v162 offset:55296
	ds_read_b128 v[248:251], v162 offset:56320
	global_load_lds_dwordx4 v[150:151], off
	s_add_i32 m0, s24, 0x2000
	s_add_u32 s22, s22, 0x40080
	v_lshl_add_u64 v[150:151], v[208:209], 0, s[96:97]
	s_addc_u32 s23, s23, 0
	s_add_i32 s24, s47, s28
	global_load_lds_dwordx4 v[150:151], off
	v_lshl_add_u64 v[150:151], s[22:23], 0, v[134:135]
	s_mov_b32 m0, s24
	s_nop 0
	global_load_lds_dwordx4 v[150:151], off
	v_lshl_add_u64 v[150:151], s[22:23], 0, v[130:131]
	s_add_i32 m0, s24, 0x2000
	s_nop 0
	global_load_lds_dwordx4 v[150:151], off
	v_lshl_add_u64 v[150:151], v[224:225], 0, s[96:97]
	s_mov_b32 m0, s36
	s_nop 0
	global_load_lds_dwordx4 v[150:151], off
	v_lshl_add_u64 v[150:151], v[252:253], 0, s[96:97]
	s_mov_b32 m0, s37
	s_nop 0
	global_load_lds_dwordx4 v[150:151], off
	s_nop 0
	s_nop 0
	s_waitcnt vmcnt(8)
	s_waitcnt lgkmcnt(0)
	s_barrier
	s_waitcnt lgkmcnt(0)
	v_mfma_f32_16x16x32_bf16 v[62:65], v[164:167], v[196:199], v[62:65]
	v_mfma_f32_16x16x32_bf16 v[58:61], v[172:175], v[196:199], v[58:61]
	v_mfma_f32_16x16x32_bf16 v[54:57], v[164:167], v[204:207], v[54:57]
	v_mfma_f32_16x16x32_bf16 v[50:53], v[172:175], v[204:207], v[50:53]
	v_mfma_f32_16x16x32_bf16 v[46:49], v[164:167], v[236:239], v[46:49]
	v_mfma_f32_16x16x32_bf16 v[42:45], v[172:175], v[236:239], v[42:45]
	v_mfma_f32_16x16x32_bf16 v[38:41], v[164:167], v[244:247], v[38:41]
	v_mfma_f32_16x16x32_bf16 v[34:37], v[172:175], v[244:247], v[34:37]
	v_mfma_f32_16x16x32_bf16 v[62:65], v[168:171], v[200:203], v[62:65]
	v_mfma_f32_16x16x32_bf16 v[58:61], v[176:179], v[200:203], v[58:61]
	v_mfma_f32_16x16x32_bf16 v[54:57], v[168:171], v[220:223], v[54:57]
	v_mfma_f32_16x16x32_bf16 v[50:53], v[176:179], v[220:223], v[50:53]
	v_mfma_f32_16x16x32_bf16 v[46:49], v[168:171], v[240:243], v[46:49]
	v_mfma_f32_16x16x32_bf16 v[42:45], v[176:179], v[240:243], v[42:45]
	v_mfma_f32_16x16x32_bf16 v[38:41], v[168:171], v[248:251], v[38:41]
	v_mfma_f32_16x16x32_bf16 v[34:37], v[176:179], v[248:251], v[34:37]
	v_mfma_f32_16x16x32_bf16 v[30:33], v[180:183], v[196:199], v[30:33]
	v_mfma_f32_16x16x32_bf16 v[26:29], v[188:191], v[196:199], v[26:29]
	v_mfma_f32_16x16x32_bf16 v[22:25], v[180:183], v[204:207], v[22:25]
	v_mfma_f32_16x16x32_bf16 v[18:21], v[188:191], v[204:207], v[18:21]
	v_mfma_f32_16x16x32_bf16 v[14:17], v[180:183], v[236:239], v[14:17]
	v_mfma_f32_16x16x32_bf16 v[10:13], v[188:191], v[236:239], v[10:13]
	v_mfma_f32_16x16x32_bf16 v[6:9], v[180:183], v[244:247], v[6:9]
	v_mfma_f32_16x16x32_bf16 v[2:5], v[188:191], v[244:247], v[2:5]
	v_mfma_f32_16x16x32_bf16 v[30:33], v[184:187], v[200:203], v[30:33]
	v_mfma_f32_16x16x32_bf16 v[26:29], v[192:195], v[200:203], v[26:29]
	v_mfma_f32_16x16x32_bf16 v[22:25], v[184:187], v[220:223], v[22:25]
	v_mfma_f32_16x16x32_bf16 v[18:21], v[192:195], v[220:223], v[18:21]
	v_mfma_f32_16x16x32_bf16 v[14:17], v[184:187], v[240:243], v[14:17]
	v_mfma_f32_16x16x32_bf16 v[10:13], v[192:195], v[240:243], v[10:13]
	v_mfma_f32_16x16x32_bf16 v[6:9], v[184:187], v[248:251], v[6:9]
	v_mfma_f32_16x16x32_bf16 v[2:5], v[192:195], v[248:251], v[2:5]
	s_barrier
	s_add_i32 s45, s45, 2
	s_add_u32 s43, s43, 0x100
	s_addc_u32 s44, s44, 0
	s_add_u32 s20, s20, 0x100
	s_addc_u32 s21, s21, 0
	s_cmp_gt_u32 s45, 13
.LBB0_640:
	s_add_u32 s22, s20, 0xfffc0080
	s_addc_u32 s23, s21, -1
	s_add_i32 s46, 0, 0x10000
	s_cmp_eq_u32 s45, 12
	s_cselect_b32 s25, s13, s23
	s_cselect_b32 s24, s19, s22
	v_add_u32_e32 v150, s46, v159
	s_cselect_b32 s23, s11, s44
	s_cselect_b32 s22, s41, s43
	s_add_i32 s48, 0, 0x14000
	ds_read_b128 v[164:167], v150
	ds_read_b128 v[168:171], v150 offset:1024
	ds_read_b128 v[172:175], v150 offset:2048
	ds_read_b128 v[176:179], v150 offset:3072
	v_add_u32_e32 v150, s48, v159
	ds_read_b128 v[180:183], v150
	ds_read_b128 v[184:187], v150 offset:1024
	ds_read_b128 v[188:191], v150 offset:2048
	ds_read_b128 v[192:195], v150 offset:3072
	v_lshl_add_u64 v[150:151], s[20:21], 0, v[140:141]
	s_add_i32 m0, s30, 0xc000
	ds_read_b128 v[196:199], v162
	ds_read_b128 v[200:203], v162 offset:1024
	ds_read_b128 v[204:207], v162 offset:2048
	ds_read_b128 v[220:223], v162 offset:3072
	ds_read_b128 v[236:239], v162 offset:4096
	ds_read_b128 v[240:243], v162 offset:5120
	ds_read_b128 v[244:247], v162 offset:6144
	ds_read_b128 v[248:251], v162 offset:7168
	global_load_lds_dwordx4 v[150:151], off
	v_lshl_add_u64 v[150:151], s[20:21], 0, v[138:139]
	s_add_i32 m0, s30, 0xe000
	s_nop 0
	global_load_lds_dwordx4 v[150:151], off
	s_branch .Lpadj_13
	s_nop 0
	s_nop 0
	s_nop 0
	s_nop 0
	s_nop 0
	s_nop 0
	s_nop 0
.Lpadj_13:
	s_waitcnt vmcnt(8)
	s_waitcnt lgkmcnt(0)
	s_barrier
	s_waitcnt lgkmcnt(0)
	v_mfma_f32_16x16x32_bf16 v[126:129], v[164:167], v[196:199], v[126:129]
	v_mfma_f32_16x16x32_bf16 v[122:125], v[172:175], v[196:199], v[122:125]
	v_mfma_f32_16x16x32_bf16 v[118:121], v[164:167], v[204:207], v[118:121]
	v_mfma_f32_16x16x32_bf16 v[114:117], v[172:175], v[204:207], v[114:117]
	v_mfma_f32_16x16x32_bf16 v[110:113], v[164:167], v[236:239], v[110:113]
	v_mfma_f32_16x16x32_bf16 v[106:109], v[172:175], v[236:239], v[106:109]
	v_mfma_f32_16x16x32_bf16 v[102:105], v[164:167], v[244:247], v[102:105]
	v_mfma_f32_16x16x32_bf16 v[98:101], v[172:175], v[244:247], v[98:101]
	v_mfma_f32_16x16x32_bf16 v[126:129], v[168:171], v[200:203], v[126:129]
	v_mfma_f32_16x16x32_bf16 v[122:125], v[176:179], v[200:203], v[122:125]
	v_mfma_f32_16x16x32_bf16 v[118:121], v[168:171], v[220:223], v[118:121]
	v_mfma_f32_16x16x32_bf16 v[114:117], v[176:179], v[220:223], v[114:117]
	v_mfma_f32_16x16x32_bf16 v[110:113], v[168:171], v[240:243], v[110:113]
	v_mfma_f32_16x16x32_bf16 v[106:109], v[176:179], v[240:243], v[106:109]
	v_mfma_f32_16x16x32_bf16 v[102:105], v[168:171], v[248:251], v[102:105]
	v_mfma_f32_16x16x32_bf16 v[98:101], v[176:179], v[248:251], v[98:101]
	v_mfma_f32_16x16x32_bf16 v[94:97], v[180:183], v[196:199], v[94:97]
	v_mfma_f32_16x16x32_bf16 v[90:93], v[188:191], v[196:199], v[90:93]
	v_mfma_f32_16x16x32_bf16 v[86:89], v[180:183], v[204:207], v[86:89]
	v_mfma_f32_16x16x32_bf16 v[82:85], v[188:191], v[204:207], v[82:85]
	v_mfma_f32_16x16x32_bf16 v[78:81], v[180:183], v[236:239], v[78:81]
	v_mfma_f32_16x16x32_bf16 v[74:77], v[188:191], v[236:239], v[74:77]
	v_mfma_f32_16x16x32_bf16 v[70:73], v[180:183], v[244:247], v[70:73]
	v_mfma_f32_16x16x32_bf16 v[66:69], v[188:191], v[244:247], v[66:69]
	v_mfma_f32_16x16x32_bf16 v[94:97], v[184:187], v[200:203], v[94:97]
	v_mfma_f32_16x16x32_bf16 v[90:93], v[192:195], v[200:203], v[90:93]
	v_mfma_f32_16x16x32_bf16 v[86:89], v[184:187], v[220:223], v[86:89]
	v_mfma_f32_16x16x32_bf16 v[82:85], v[192:195], v[220:223], v[82:85]
	v_mfma_f32_16x16x32_bf16 v[78:81], v[184:187], v[240:243], v[78:81]
	v_mfma_f32_16x16x32_bf16 v[74:77], v[192:195], v[240:243], v[74:77]
	v_mfma_f32_16x16x32_bf16 v[70:73], v[184:187], v[248:251], v[70:73]
	v_mfma_f32_16x16x32_bf16 v[66:69], v[192:195], v[248:251], v[66:69]
	s_barrier
	s_add_i32 s46, s46, s28
	v_lshl_add_u64 v[150:151], s[22:23], 0, v[134:135]
	s_mov_b32 m0, s46
	ds_read_b128 v[196:199], v162 offset:16384
	ds_read_b128 v[200:203], v162 offset:17408
	ds_read_b128 v[204:207], v162 offset:18432
	ds_read_b128 v[220:223], v162 offset:19456
	ds_read_b128 v[236:239], v162 offset:20480
	ds_read_b128 v[240:243], v162 offset:21504
	ds_read_b128 v[244:247], v162 offset:22528
	ds_read_b128 v[248:251], v162 offset:23552
	global_load_lds_dwordx4 v[150:151], off
	s_add_i32 m0, s46, 0x2000
	s_add_u32 s46, s22, 0x40000
	v_lshl_add_u64 v[208:209], s[22:23], 0, v[130:131]
	s_addc_u32 s47, s23, 0
	s_add_i32 s48, s48, s28
	global_load_lds_dwordx4 v[208:209], off
	v_lshl_add_u64 v[224:225], s[46:47], 0, v[134:135]
	s_mov_b32 m0, s48
	v_lshl_add_u64 v[252:253], s[24:25], 0, v[132:133]
	global_load_lds_dwordx4 v[224:225], off
	v_lshl_add_u64 v[224:225], s[46:47], 0, v[130:131]
	s_add_i32 m0, s48, 0x2000
	s_nop 0
	global_load_lds_dwordx4 v[224:225], off
	v_lshl_add_u64 v[224:225], s[24:25], 0, v[136:137]
	s_mov_b32 m0, s30
	s_nop 0
	global_load_lds_dwordx4 v[224:225], off
	s_mov_b32 m0, s31
	s_nop 0
	global_load_lds_dwordx4 v[252:253], off
	s_nop 0
	s_nop 0
	s_nop 0
	s_waitcnt vmcnt(8)
	s_waitcnt lgkmcnt(0)
	s_barrier
	s_waitcnt lgkmcnt(0)
	v_mfma_f32_16x16x32_bf16 v[62:65], v[164:167], v[196:199], v[62:65]
	v_mfma_f32_16x16x32_bf16 v[58:61], v[172:175], v[196:199], v[58:61]
	v_mfma_f32_16x16x32_bf16 v[54:57], v[164:167], v[204:207], v[54:57]
	v_mfma_f32_16x16x32_bf16 v[50:53], v[172:175], v[204:207], v[50:53]
	v_mfma_f32_16x16x32_bf16 v[46:49], v[164:167], v[236:239], v[46:49]
	v_mfma_f32_16x16x32_bf16 v[42:45], v[172:175], v[236:239], v[42:45]
	v_mfma_f32_16x16x32_bf16 v[38:41], v[164:167], v[244:247], v[38:41]
	v_mfma_f32_16x16x32_bf16 v[34:37], v[172:175], v[244:247], v[34:37]
	v_mfma_f32_16x16x32_bf16 v[62:65], v[168:171], v[200:203], v[62:65]
	v_mfma_f32_16x16x32_bf16 v[58:61], v[176:179], v[200:203], v[58:61]
	v_mfma_f32_16x16x32_bf16 v[54:57], v[168:171], v[220:223], v[54:57]
	v_mfma_f32_16x16x32_bf16 v[50:53], v[176:179], v[220:223], v[50:53]
	v_mfma_f32_16x16x32_bf16 v[46:49], v[168:171], v[240:243], v[46:49]
	v_mfma_f32_16x16x32_bf16 v[42:45], v[176:179], v[240:243], v[42:45]
	v_mfma_f32_16x16x32_bf16 v[38:41], v[168:171], v[248:251], v[38:41]
	v_mfma_f32_16x16x32_bf16 v[34:37], v[176:179], v[248:251], v[34:37]
	v_mfma_f32_16x16x32_bf16 v[30:33], v[180:183], v[196:199], v[30:33]
	v_mfma_f32_16x16x32_bf16 v[26:29], v[188:191], v[196:199], v[26:29]
	v_mfma_f32_16x16x32_bf16 v[22:25], v[180:183], v[204:207], v[22:25]
	v_mfma_f32_16x16x32_bf16 v[18:21], v[188:191], v[204:207], v[18:21]
	v_mfma_f32_16x16x32_bf16 v[14:17], v[180:183], v[236:239], v[14:17]
	v_mfma_f32_16x16x32_bf16 v[10:13], v[188:191], v[236:239], v[10:13]
	v_mfma_f32_16x16x32_bf16 v[6:9], v[180:183], v[244:247], v[6:9]
	v_mfma_f32_16x16x32_bf16 v[2:5], v[188:191], v[244:247], v[2:5]
	v_mfma_f32_16x16x32_bf16 v[30:33], v[184:187], v[200:203], v[30:33]
	v_mfma_f32_16x16x32_bf16 v[26:29], v[192:195], v[200:203], v[26:29]
	v_mfma_f32_16x16x32_bf16 v[22:25], v[184:187], v[220:223], v[22:25]
	v_mfma_f32_16x16x32_bf16 v[18:21], v[192:195], v[220:223], v[18:21]
	v_mfma_f32_16x16x32_bf16 v[14:17], v[184:187], v[240:243], v[14:17]
	v_mfma_f32_16x16x32_bf16 v[10:13], v[192:195], v[240:243], v[10:13]
	v_mfma_f32_16x16x32_bf16 v[6:9], v[184:187], v[248:251], v[6:9]
	v_mfma_f32_16x16x32_bf16 v[2:5], v[192:195], v[248:251], v[2:5]
	s_barrier
	s_add_i32 s46, 0, 0x18000
	v_add_u32_e32 v163, s46, v159
	s_add_i32 s47, 0, 0x1c000
	ds_read_b128 v[164:167], v163
	ds_read_b128 v[168:171], v163 offset:1024
	ds_read_b128 v[172:175], v163 offset:2048
	ds_read_b128 v[176:179], v163 offset:3072
	v_add_u32_e32 v163, s47, v159
	ds_read_b128 v[180:183], v163
	ds_read_b128 v[184:187], v163 offset:1024
	ds_read_b128 v[188:191], v163 offset:2048
	ds_read_b128 v[192:195], v163 offset:3072
	s_add_u32 s24, s24, 0x40000
	s_addc_u32 s25, s25, 0
	s_mov_b32 m0, s34
	v_lshl_add_u64 v[230:231], s[24:25], 0, v[136:137]
	ds_read_b128 v[196:199], v162 offset:32768
	ds_read_b128 v[200:203], v162 offset:33792
	ds_read_b128 v[204:207], v162 offset:34816
	ds_read_b128 v[220:223], v162 offset:35840
	ds_read_b128 v[236:239], v162 offset:36864
	ds_read_b128 v[240:243], v162 offset:37888
	ds_read_b128 v[244:247], v162 offset:38912
	ds_read_b128 v[248:251], v162 offset:39936
	global_load_lds_dwordx4 v[230:231], off
	v_lshl_add_u64 v[230:231], s[24:25], 0, v[132:133]
	s_mov_b32 m0, s35
	s_nop 0
	global_load_lds_dwordx4 v[230:231], off
	s_branch .Lpadj_14
	s_nop 0
	s_nop 0
	s_nop 0
	s_nop 0
	s_nop 0
	s_nop 0
.Lpadj_14:
	s_waitcnt vmcnt(8)
	s_waitcnt lgkmcnt(0)
	s_barrier
	s_waitcnt lgkmcnt(0)
	v_mfma_f32_16x16x32_bf16 v[126:129], v[164:167], v[196:199], v[126:129]
	v_mfma_f32_16x16x32_bf16 v[122:125], v[172:175], v[196:199], v[122:125]
	v_mfma_f32_16x16x32_bf16 v[118:121], v[164:167], v[204:207], v[118:121]
	v_mfma_f32_16x16x32_bf16 v[114:117], v[172:175], v[204:207], v[114:117]
	v_mfma_f32_16x16x32_bf16 v[110:113], v[164:167], v[236:239], v[110:113]
	v_mfma_f32_16x16x32_bf16 v[106:109], v[172:175], v[236:239], v[106:109]
	v_mfma_f32_16x16x32_bf16 v[102:105], v[164:167], v[244:247], v[102:105]
	v_mfma_f32_16x16x32_bf16 v[98:101], v[172:175], v[244:247], v[98:101]
	v_mfma_f32_16x16x32_bf16 v[126:129], v[168:171], v[200:203], v[126:129]
	v_mfma_f32_16x16x32_bf16 v[122:125], v[176:179], v[200:203], v[122:125]
	v_mfma_f32_16x16x32_bf16 v[118:121], v[168:171], v[220:223], v[118:121]
	v_mfma_f32_16x16x32_bf16 v[114:117], v[176:179], v[220:223], v[114:117]
	v_mfma_f32_16x16x32_bf16 v[110:113], v[168:171], v[240:243], v[110:113]
	v_mfma_f32_16x16x32_bf16 v[106:109], v[176:179], v[240:243], v[106:109]
	v_mfma_f32_16x16x32_bf16 v[102:105], v[168:171], v[248:251], v[102:105]
	v_mfma_f32_16x16x32_bf16 v[98:101], v[176:179], v[248:251], v[98:101]
	v_mfma_f32_16x16x32_bf16 v[94:97], v[180:183], v[196:199], v[94:97]
	v_mfma_f32_16x16x32_bf16 v[90:93], v[188:191], v[196:199], v[90:93]
	v_mfma_f32_16x16x32_bf16 v[86:89], v[180:183], v[204:207], v[86:89]
	v_mfma_f32_16x16x32_bf16 v[82:85], v[188:191], v[204:207], v[82:85]
	v_mfma_f32_16x16x32_bf16 v[78:81], v[180:183], v[236:239], v[78:81]
	v_mfma_f32_16x16x32_bf16 v[74:77], v[188:191], v[236:239], v[74:77]
	v_mfma_f32_16x16x32_bf16 v[70:73], v[180:183], v[244:247], v[70:73]
	v_mfma_f32_16x16x32_bf16 v[66:69], v[188:191], v[244:247], v[66:69]
	v_mfma_f32_16x16x32_bf16 v[94:97], v[184:187], v[200:203], v[94:97]
	v_mfma_f32_16x16x32_bf16 v[90:93], v[192:195], v[200:203], v[90:93]
	v_mfma_f32_16x16x32_bf16 v[86:89], v[184:187], v[220:223], v[86:89]
	v_mfma_f32_16x16x32_bf16 v[82:85], v[192:195], v[220:223], v[82:85]
	v_mfma_f32_16x16x32_bf16 v[78:81], v[184:187], v[240:243], v[78:81]
	v_mfma_f32_16x16x32_bf16 v[74:77], v[192:195], v[240:243], v[74:77]
	v_mfma_f32_16x16x32_bf16 v[70:73], v[184:187], v[248:251], v[70:73]
	v_mfma_f32_16x16x32_bf16 v[66:69], v[192:195], v[248:251], v[66:69]
	s_barrier
	s_add_i32 s24, s46, s28
	v_lshl_add_u64 v[150:151], v[150:151], 0, s[96:97]
	s_mov_b32 m0, s24
	ds_read_b128 v[196:199], v162 offset:49152
	ds_read_b128 v[200:203], v162 offset:50176
	ds_read_b128 v[204:207], v162 offset:51200
	ds_read_b128 v[220:223], v162 offset:52224
	ds_read_b128 v[236:239], v162 offset:53248
	ds_read_b128 v[240:243], v162 offset:54272
	ds_read_b128 v[244:247], v162 offset:55296
	ds_read_b128 v[248:251], v162 offset:56320
	global_load_lds_dwordx4 v[150:151], off
	s_add_i32 m0, s24, 0x2000
	s_add_u32 s22, s22, 0x40080
	v_lshl_add_u64 v[150:151], v[208:209], 0, s[96:97]
	s_addc_u32 s23, s23, 0
	s_add_i32 s24, s47, s28
	global_load_lds_dwordx4 v[150:151], off
	v_lshl_add_u64 v[150:151], s[22:23], 0, v[134:135]
	s_mov_b32 m0, s24
	s_nop 0
	global_load_lds_dwordx4 v[150:151], off
	v_lshl_add_u64 v[150:151], s[22:23], 0, v[130:131]
	s_add_i32 m0, s24, 0x2000
	s_nop 0
	global_load_lds_dwordx4 v[150:151], off
	v_lshl_add_u64 v[150:151], v[224:225], 0, s[96:97]
	s_mov_b32 m0, s36
	s_nop 0
	global_load_lds_dwordx4 v[150:151], off
	v_lshl_add_u64 v[150:151], v[252:253], 0, s[96:97]
	s_mov_b32 m0, s37
	s_nop 0
	global_load_lds_dwordx4 v[150:151], off
	s_nop 0
	s_nop 0
	s_waitcnt vmcnt(8)
	s_waitcnt lgkmcnt(0)
	s_barrier
	s_waitcnt lgkmcnt(0)
	v_mfma_f32_16x16x32_bf16 v[62:65], v[164:167], v[196:199], v[62:65]
	v_mfma_f32_16x16x32_bf16 v[58:61], v[172:175], v[196:199], v[58:61]
	v_mfma_f32_16x16x32_bf16 v[54:57], v[164:167], v[204:207], v[54:57]
	v_mfma_f32_16x16x32_bf16 v[50:53], v[172:175], v[204:207], v[50:53]
	v_mfma_f32_16x16x32_bf16 v[46:49], v[164:167], v[236:239], v[46:49]
	v_mfma_f32_16x16x32_bf16 v[42:45], v[172:175], v[236:239], v[42:45]
	v_mfma_f32_16x16x32_bf16 v[38:41], v[164:167], v[244:247], v[38:41]
	v_mfma_f32_16x16x32_bf16 v[34:37], v[172:175], v[244:247], v[34:37]
	v_mfma_f32_16x16x32_bf16 v[62:65], v[168:171], v[200:203], v[62:65]
	v_mfma_f32_16x16x32_bf16 v[58:61], v[176:179], v[200:203], v[58:61]
	v_mfma_f32_16x16x32_bf16 v[54:57], v[168:171], v[220:223], v[54:57]
	v_mfma_f32_16x16x32_bf16 v[50:53], v[176:179], v[220:223], v[50:53]
	v_mfma_f32_16x16x32_bf16 v[46:49], v[168:171], v[240:243], v[46:49]
	v_mfma_f32_16x16x32_bf16 v[42:45], v[176:179], v[240:243], v[42:45]
	v_mfma_f32_16x16x32_bf16 v[38:41], v[168:171], v[248:251], v[38:41]
	v_mfma_f32_16x16x32_bf16 v[34:37], v[176:179], v[248:251], v[34:37]
	v_mfma_f32_16x16x32_bf16 v[30:33], v[180:183], v[196:199], v[30:33]
	v_mfma_f32_16x16x32_bf16 v[26:29], v[188:191], v[196:199], v[26:29]
	v_mfma_f32_16x16x32_bf16 v[22:25], v[180:183], v[204:207], v[22:25]
	v_mfma_f32_16x16x32_bf16 v[18:21], v[188:191], v[204:207], v[18:21]
	v_mfma_f32_16x16x32_bf16 v[14:17], v[180:183], v[236:239], v[14:17]
	v_mfma_f32_16x16x32_bf16 v[10:13], v[188:191], v[236:239], v[10:13]
	v_mfma_f32_16x16x32_bf16 v[6:9], v[180:183], v[244:247], v[6:9]
	v_mfma_f32_16x16x32_bf16 v[2:5], v[188:191], v[244:247], v[2:5]
	v_mfma_f32_16x16x32_bf16 v[30:33], v[184:187], v[200:203], v[30:33]
	v_mfma_f32_16x16x32_bf16 v[26:29], v[192:195], v[200:203], v[26:29]
	v_mfma_f32_16x16x32_bf16 v[22:25], v[184:187], v[220:223], v[22:25]
	v_mfma_f32_16x16x32_bf16 v[18:21], v[192:195], v[220:223], v[18:21]
	v_mfma_f32_16x16x32_bf16 v[14:17], v[184:187], v[240:243], v[14:17]
	v_mfma_f32_16x16x32_bf16 v[10:13], v[192:195], v[240:243], v[10:13]
	v_mfma_f32_16x16x32_bf16 v[6:9], v[184:187], v[248:251], v[6:9]
	v_mfma_f32_16x16x32_bf16 v[2:5], v[192:195], v[248:251], v[2:5]
	s_barrier
	s_add_i32 s45, s45, 2
	s_add_u32 s43, s43, 0x100
	s_addc_u32 s44, s44, 0
	s_add_u32 s20, s20, 0x100
	s_addc_u32 s21, s21, 0
	s_cmp_gt_u32 s45, 13
	s_cbranch_scc0 .LBB0_640
	s_and_b64 vcc, exec, s[8:9]
	s_cbranch_vccz .LBB0_643
	s_barrier
